# plus GEMM K-loop LDS-DMA in saddr form (drops 8 of 16 64-bit VALU address adds per iteration)
# speedup vs baseline: 1.0051x; 1.0051x over previous
; #define PG8_STAGE(bufoff, gbase, voff) do { _Pragma("unroll") for (int _i = 0; _i < 2; ++_i) \
;         __builtin_amdgcn_global_load_lds((const unsigned*)((const char*)(gbase) + (voff)[_i]), (PG8_LAS unsigned*)(lds + (bufoff) + ldsw + _i * 8192), 16, 0, 0); } while (0)
; #define PG8_LDA(dst, b, h) do { _Pragma("unroll") for (int m = 0; m < 4; ++m) _Pragma("unroll") for (int k = 0; k < 2; ++k) dst[m][k] = *(const PG8_LAS bf16x8*)(lds + PG8_SA(b, h) + aoff + m * 2048 + k * 1024); } while (0)
; #define PG8_LDB(dst, b, h) do { _Pragma("unroll") for (int n = 0; n < 2; ++n) _Pragma("unroll") for (int k = 0; k < 2; ++k) dst[n][k] = *(const PG8_LAS bf16x8*)(lds + PG8_SB(b, h) + boff + n * 2048 + k * 1024); } while (0)
; #define PG8_MMA(ai, bj, At, Bt) do { __builtin_amdgcn_s_setprio(1); _Pragma("unroll") for (int m = 0; m < 4; ++m) _Pragma("unroll") for (int n = 0; n < 2; ++n) _Pragma("unroll") for (int k = 0; k < 2; ++k) \
;         acc[ai][bj][m][n] = __builtin_amdgcn_mfma_f32_16x16x32_bf16(Bt[n][k], At[m][k], acc[ai][bj][m][n], 0, 0, 0); __builtin_amdgcn_s_setprio(0); } while (0)
; #define PG8_WAIT_V(n) asm volatile("s_waitcnt vmcnt(" #n ")" ::: "memory")
; #define PG8_BAR __builtin_amdgcn_s_barrier()
; template <class Epi, class Sched, bool ALIGN_EPI = false, bool SP2 = false>
; __device__ __forceinline__ void gemm_phase(PG8_LAS unsigned char* lds, const Gemm g, const Sched& S, const Epi& E, const int wid) {
;     ...
;         for (int t = 0; t < nt; t += 2) {
;             const bool last = (t == nt - 2);
;             const char* a1 = cA + (size_t)(t + 1) * kstep;
;             const char* a2 = last ? nA : cA + (size_t)(t + 2) * kstep; const char* b2 = last ? nB : cB + (size_t)(t + 2) * kstep;
;             const char* a3 = a2 + kstep; const char* b3 = b2 + kstep;
;             if (last && has_next) S.a_ready(nxt);
;             if constexpr (SP2) {
;             PG8_LDB(B0, 0, 0); PG8_LDB(B1, 0, 1); PG8_SCHED; PG8_LDA(At, 0, 0); PG8_STAGE(PG8_SA(1, 1), a1 + hstep, voffA);
;             PG8_WAIT_V(8); PG8_WAIT_L(0); PG8_BAR; PG8_MMA(0, 0, At, B0); PG8_MMA(0, 1, At, B1); PG8_BAR; PG8_SCHED;
;             PG8_LDA(At, 0, 1); PG8_STAGE(PG8_SB(0, 0), b2, voffB); PG8_STAGE(PG8_SB(0, 1), b2 + hstep, voffB); PG8_STAGE(PG8_SA(0, 0), a2, voffA);
;             PG8_WAIT_V(8); PG8_WAIT_L(0); PG8_BAR; PG8_MMA(1, 0, At, B0); PG8_MMA(1, 1, At, B1); PG8_BAR; PG8_SCHED;
.LBB0_204:
	ds_read_b128 v[144:147], v151
	ds_read_b128 v[154:157], v151 offset:1024
	ds_read_b128 v[158:161], v151 offset:2048
	ds_read_b128 v[162:165], v151 offset:3072
	ds_read_b128 v[166:169], v152
	ds_read_b128 v[170:173], v152 offset:1024
	ds_read_b128 v[174:177], v152 offset:2048
	ds_read_b128 v[178:181], v152 offset:3072
	s_add_u32 s26, s24, 0xfffc0080
	s_addc_u32 s27, s25, -1
	s_cmp_eq_u32 s56, 12
	s_cselect_b32 s29, s17, s27
	s_cselect_b32 s28, s52, s26
	s_cselect_b32 s27, s15, s55
	s_cselect_b32 s26, s53, s54
	s_add_i32 m0, s23, 0xc000
	ds_read_b128 v[182:185], v153
	ds_read_b128 v[186:189], v153 offset:1024
	ds_read_b128 v[190:193], v153 offset:2048
	ds_read_b128 v[194:197], v153 offset:3072
	ds_read_b128 v[198:201], v153 offset:4096
	ds_read_b128 v[202:205], v153 offset:5120
	ds_read_b128 v[206:209], v153 offset:6144
	ds_read_b128 v[210:213], v153 offset:7168
	global_load_lds_dwordx4 v136, s[24:25]
	s_add_i32 m0, s23, 0xe000
	s_nop 0
	global_load_lds_dwordx4 v138, s[24:25]
	s_waitcnt vmcnt(8)
	s_waitcnt lgkmcnt(0)
	s_barrier
	s_setprio 1
	s_waitcnt lgkmcnt(0)
	v_mfma_f32_16x16x32_bf16 v[124:127], v[144:147], v[182:185], v[124:127]
	v_mfma_f32_16x16x32_bf16 v[120:123], v[158:161], v[182:185], v[120:123]
	v_mfma_f32_16x16x32_bf16 v[116:119], v[144:147], v[190:193], v[116:119]
	v_mfma_f32_16x16x32_bf16 v[108:111], v[158:161], v[190:193], v[108:111]
	v_mfma_f32_16x16x32_bf16 v[100:103], v[144:147], v[198:201], v[100:103]
	v_mfma_f32_16x16x32_bf16 v[92:95], v[158:161], v[198:201], v[92:95]
	v_mfma_f32_16x16x32_bf16 v[84:87], v[144:147], v[206:209], v[84:87]
	v_mfma_f32_16x16x32_bf16 v[76:79], v[158:161], v[206:209], v[76:79]
	v_mfma_f32_16x16x32_bf16 v[124:127], v[154:157], v[186:189], v[124:127]
	v_mfma_f32_16x16x32_bf16 v[120:123], v[162:165], v[186:189], v[120:123]
	v_mfma_f32_16x16x32_bf16 v[116:119], v[154:157], v[194:197], v[116:119]
	v_mfma_f32_16x16x32_bf16 v[108:111], v[162:165], v[194:197], v[108:111]
	v_mfma_f32_16x16x32_bf16 v[100:103], v[154:157], v[202:205], v[100:103]
	v_mfma_f32_16x16x32_bf16 v[92:95], v[162:165], v[202:205], v[92:95]
	v_mfma_f32_16x16x32_bf16 v[84:87], v[154:157], v[210:213], v[84:87]
	v_mfma_f32_16x16x32_bf16 v[76:79], v[162:165], v[210:213], v[76:79]
	s_setprio 0
	s_setprio 1
	v_mfma_f32_16x16x32_bf16 v[112:115], v[166:169], v[182:185], v[112:115]
	v_mfma_f32_16x16x32_bf16 v[104:107], v[174:177], v[182:185], v[104:107]
	v_mfma_f32_16x16x32_bf16 v[96:99], v[166:169], v[190:193], v[96:99]
	v_mfma_f32_16x16x32_bf16 v[88:91], v[174:177], v[190:193], v[88:91]
	v_mfma_f32_16x16x32_bf16 v[80:83], v[166:169], v[198:201], v[80:83]
	v_mfma_f32_16x16x32_bf16 v[72:75], v[174:177], v[198:201], v[72:75]
	v_mfma_f32_16x16x32_bf16 v[68:71], v[166:169], v[206:209], v[68:71]
	v_mfma_f32_16x16x32_bf16 v[64:67], v[174:177], v[206:209], v[64:67]
	v_mfma_f32_16x16x32_bf16 v[112:115], v[170:173], v[186:189], v[112:115]
	v_mfma_f32_16x16x32_bf16 v[104:107], v[178:181], v[186:189], v[104:107]
	v_mfma_f32_16x16x32_bf16 v[96:99], v[170:173], v[194:197], v[96:99]
	v_mfma_f32_16x16x32_bf16 v[88:91], v[178:181], v[194:197], v[88:91]
	v_mfma_f32_16x16x32_bf16 v[80:83], v[170:173], v[202:205], v[80:83]
	v_mfma_f32_16x16x32_bf16 v[72:75], v[178:181], v[202:205], v[72:75]
	v_mfma_f32_16x16x32_bf16 v[68:71], v[170:173], v[210:213], v[68:71]
	v_mfma_f32_16x16x32_bf16 v[64:67], v[178:181], v[210:213], v[64:67]
	s_setprio 0
	s_barrier
	s_add_i32 s57, s47, s34
	v_lshl_add_u64 v[214:215], s[26:27], 0, v[132:133]
	s_mov_b32 m0, s57
	ds_read_b128 v[182:185], v153 offset:16384
	ds_read_b128 v[186:189], v153 offset:17408
	ds_read_b128 v[190:193], v153 offset:18432
	ds_read_b128 v[194:197], v153 offset:19456
	ds_read_b128 v[198:201], v153 offset:20480
	ds_read_b128 v[202:205], v153 offset:21504
	ds_read_b128 v[206:209], v153 offset:22528
	ds_read_b128 v[210:213], v153 offset:23552
	global_load_lds_dwordx4 v[214:215], off
	s_add_i32 m0, s57, 0x2000
	s_add_u32 s58, s26, 0x40000
	v_lshl_add_u64 v[216:217], s[26:27], 0, v[128:129]
	s_addc_u32 s59, s27, 0
	s_add_i32 s57, s49, s34
	global_load_lds_dwordx4 v[216:217], off
	s_mov_b32 m0, s57
	v_lshl_add_u64 v[220:221], s[28:29], 0, v[130:131]
	global_load_lds_dwordx4 v132, s[58:59]
	s_add_i32 m0, s57, 0x2000
	s_nop 0
	global_load_lds_dwordx4 v128, s[58:59]
	v_lshl_add_u64 v[218:219], s[28:29], 0, v[134:135]
	s_mov_b32 m0, s23
	s_nop 0
	global_load_lds_dwordx4 v[218:219], off
	s_mov_b32 m0, s40
	s_nop 0
	global_load_lds_dwordx4 v[220:221], off
	s_waitcnt vmcnt(8)
	s_waitcnt lgkmcnt(0)
	s_barrier
; #define PG8_STAGE(bufoff, gbase, voff) do { _Pragma("unroll") for (int _i = 0; _i < 2; ++_i) \
;         __builtin_amdgcn_global_load_lds((const unsigned*)((const char*)(gbase) + (voff)[_i]), (PG8_LAS unsigned*)(lds + (bufoff) + ldsw + _i * 8192), 16, 0, 0); } while (0)
; #define PG8_LDA(dst, b, h) do { _Pragma("unroll") for (int m = 0; m < 4; ++m) _Pragma("unroll") for (int k = 0; k < 2; ++k) dst[m][k] = *(const PG8_LAS bf16x8*)(lds + PG8_SA(b, h) + aoff + m * 2048 + k * 1024); } while (0)
; #define PG8_LDB(dst, b, h) do { _Pragma("unroll") for (int n = 0; n < 2; ++n) _Pragma("unroll") for (int k = 0; k < 2; ++k) dst[n][k] = *(const PG8_LAS bf16x8*)(lds + PG8_SB(b, h) + boff + n * 2048 + k * 1024); } while (0)
; #define PG8_MMA(ai, bj, At, Bt) do { __builtin_amdgcn_s_setprio(1); _Pragma("unroll") for (int m = 0; m < 4; ++m) _Pragma("unroll") for (int n = 0; n < 2; ++n) _Pragma("unroll") for (int k = 0; k < 2; ++k) \
;         acc[ai][bj][m][n] = __builtin_amdgcn_mfma_f32_16x16x32_bf16(Bt[n][k], At[m][k], acc[ai][bj][m][n], 0, 0, 0); __builtin_amdgcn_s_setprio(0); } while (0)
; #define PG8_WAIT_V(n) asm volatile("s_waitcnt vmcnt(" #n ")" ::: "memory")
; #define PG8_WAIT_L(n) asm volatile("s_waitcnt lgkmcnt(" #n ")" ::: "memory")
; #define PG8_BAR __builtin_amdgcn_s_barrier()
; #define PG8_SCHED __builtin_amdgcn_sched_barrier(0)
; template <class Epi, class Sched, bool ALIGN_EPI = false, bool SP2 = false>
; __device__ __forceinline__ void gemm_phase(PG8_LAS unsigned char* lds, const Gemm g, const Sched& S, const Epi& E, const int wid) {
;     ...
;             PG8_WAIT_V(8); PG8_WAIT_L(0); PG8_BAR; PG8_MMA(1, 0, At, B0); PG8_MMA(1, 1, At, B1); PG8_BAR; PG8_SCHED;
;             PG8_LDB(B0, 1, 0); PG8_LDB(B1, 1, 1); PG8_SCHED; PG8_LDA(At, 1, 0); PG8_STAGE(PG8_SA(0, 1), a2 + hstep, voffA);
;             PG8_WAIT_V(8); PG8_WAIT_L(0); PG8_BAR; PG8_MMA(0, 0, At, B0); PG8_MMA(0, 1, At, B1); PG8_BAR; PG8_SCHED;
	s_setprio 1
	s_waitcnt lgkmcnt(0)
	v_mfma_f32_16x16x32_bf16 v[60:63], v[144:147], v[182:185], v[60:63]
	v_mfma_f32_16x16x32_bf16 v[56:59], v[158:161], v[182:185], v[56:59]
	v_mfma_f32_16x16x32_bf16 v[52:55], v[144:147], v[190:193], v[52:55]
	v_mfma_f32_16x16x32_bf16 v[44:47], v[158:161], v[190:193], v[44:47]
	v_mfma_f32_16x16x32_bf16 v[36:39], v[144:147], v[198:201], v[36:39]
	v_mfma_f32_16x16x32_bf16 v[28:31], v[158:161], v[198:201], v[28:31]
	v_mfma_f32_16x16x32_bf16 v[20:23], v[144:147], v[206:209], v[20:23]
	v_mfma_f32_16x16x32_bf16 v[12:15], v[158:161], v[206:209], v[12:15]
	v_mfma_f32_16x16x32_bf16 v[60:63], v[154:157], v[186:189], v[60:63]
	v_mfma_f32_16x16x32_bf16 v[56:59], v[162:165], v[186:189], v[56:59]
	v_mfma_f32_16x16x32_bf16 v[52:55], v[154:157], v[194:197], v[52:55]
	v_mfma_f32_16x16x32_bf16 v[44:47], v[162:165], v[194:197], v[44:47]
	v_mfma_f32_16x16x32_bf16 v[36:39], v[154:157], v[202:205], v[36:39]
	v_mfma_f32_16x16x32_bf16 v[28:31], v[162:165], v[202:205], v[28:31]
	v_mfma_f32_16x16x32_bf16 v[20:23], v[154:157], v[210:213], v[20:23]
	v_mfma_f32_16x16x32_bf16 v[12:15], v[162:165], v[210:213], v[12:15]
	s_setprio 0
	s_setprio 1
	v_mfma_f32_16x16x32_bf16 v[48:51], v[166:169], v[182:185], v[48:51]
	v_mfma_f32_16x16x32_bf16 v[40:43], v[174:177], v[182:185], v[40:43]
	v_mfma_f32_16x16x32_bf16 v[32:35], v[166:169], v[190:193], v[32:35]
	v_mfma_f32_16x16x32_bf16 v[24:27], v[174:177], v[190:193], v[24:27]
	v_mfma_f32_16x16x32_bf16 v[16:19], v[166:169], v[198:201], v[16:19]
	v_mfma_f32_16x16x32_bf16 v[8:11], v[174:177], v[198:201], v[8:11]
	v_mfma_f32_16x16x32_bf16 v[4:7], v[166:169], v[206:209], v[4:7]
	v_mfma_f32_16x16x32_bf16 v[0:3], v[174:177], v[206:209], v[0:3]
	v_mfma_f32_16x16x32_bf16 v[48:51], v[170:173], v[186:189], v[48:51]
	v_mfma_f32_16x16x32_bf16 v[40:43], v[178:181], v[186:189], v[40:43]
	v_mfma_f32_16x16x32_bf16 v[32:35], v[170:173], v[194:197], v[32:35]
	v_mfma_f32_16x16x32_bf16 v[24:27], v[178:181], v[194:197], v[24:27]
	v_mfma_f32_16x16x32_bf16 v[16:19], v[170:173], v[202:205], v[16:19]
	v_mfma_f32_16x16x32_bf16 v[8:11], v[178:181], v[202:205], v[8:11]
	v_mfma_f32_16x16x32_bf16 v[4:7], v[170:173], v[210:213], v[4:7]
	v_mfma_f32_16x16x32_bf16 v[0:3], v[178:181], v[210:213], v[0:3]
	s_setprio 0
	s_barrier
	s_add_i32 s57, 0, 0x18000
	s_add_i32 s58, 0, 0x1c000
	v_add_u32_e32 v162, s57, v149
	v_add_u32_e32 v178, s58, v149
	ds_read_b128 v[144:147], v162
	ds_read_b128 v[154:157], v162 offset:1024
	ds_read_b128 v[158:161], v162 offset:2048
	ds_read_b128 v[162:165], v162 offset:3072
	ds_read_b128 v[166:169], v178
	ds_read_b128 v[170:173], v178 offset:1024
	ds_read_b128 v[174:177], v178 offset:2048
	ds_read_b128 v[178:181], v178 offset:3072
	s_add_u32 s28, s28, 0x40000
	s_addc_u32 s29, s29, 0
	s_mov_b32 m0, s41
	ds_read_b128 v[182:185], v153 offset:32768
	ds_read_b128 v[186:189], v153 offset:33792
	ds_read_b128 v[190:193], v153 offset:34816
	ds_read_b128 v[194:197], v153 offset:35840
	ds_read_b128 v[198:201], v153 offset:36864
	ds_read_b128 v[202:205], v153 offset:37888
	ds_read_b128 v[206:209], v153 offset:38912
	ds_read_b128 v[210:213], v153 offset:39936
	global_load_lds_dwordx4 v134, s[28:29]
	s_mov_b32 m0, s42
	s_nop 0
	global_load_lds_dwordx4 v130, s[28:29]
	s_waitcnt vmcnt(8)
	s_waitcnt lgkmcnt(0)
	s_barrier
	s_setprio 1
	s_waitcnt lgkmcnt(0)
	v_mfma_f32_16x16x32_bf16 v[124:127], v[144:147], v[182:185], v[124:127]
	v_mfma_f32_16x16x32_bf16 v[120:123], v[158:161], v[182:185], v[120:123]
	v_mfma_f32_16x16x32_bf16 v[116:119], v[144:147], v[190:193], v[116:119]
	v_mfma_f32_16x16x32_bf16 v[108:111], v[158:161], v[190:193], v[108:111]
	v_mfma_f32_16x16x32_bf16 v[100:103], v[144:147], v[198:201], v[100:103]
	v_mfma_f32_16x16x32_bf16 v[92:95], v[158:161], v[198:201], v[92:95]
	v_mfma_f32_16x16x32_bf16 v[84:87], v[144:147], v[206:209], v[84:87]
	v_mfma_f32_16x16x32_bf16 v[76:79], v[158:161], v[206:209], v[76:79]
	v_mfma_f32_16x16x32_bf16 v[124:127], v[154:157], v[186:189], v[124:127]
	v_mfma_f32_16x16x32_bf16 v[120:123], v[162:165], v[186:189], v[120:123]
	v_mfma_f32_16x16x32_bf16 v[116:119], v[154:157], v[194:197], v[116:119]
	v_mfma_f32_16x16x32_bf16 v[108:111], v[162:165], v[194:197], v[108:111]
	v_mfma_f32_16x16x32_bf16 v[100:103], v[154:157], v[202:205], v[100:103]
	v_mfma_f32_16x16x32_bf16 v[92:95], v[162:165], v[202:205], v[92:95]
	v_mfma_f32_16x16x32_bf16 v[84:87], v[154:157], v[210:213], v[84:87]
	v_mfma_f32_16x16x32_bf16 v[76:79], v[162:165], v[210:213], v[76:79]
	s_setprio 0
	s_setprio 1
	v_mfma_f32_16x16x32_bf16 v[112:115], v[166:169], v[182:185], v[112:115]
	v_mfma_f32_16x16x32_bf16 v[104:107], v[174:177], v[182:185], v[104:107]
	v_mfma_f32_16x16x32_bf16 v[96:99], v[166:169], v[190:193], v[96:99]
	v_mfma_f32_16x16x32_bf16 v[88:91], v[174:177], v[190:193], v[88:91]
	v_mfma_f32_16x16x32_bf16 v[80:83], v[166:169], v[198:201], v[80:83]
	v_mfma_f32_16x16x32_bf16 v[72:75], v[174:177], v[198:201], v[72:75]
	v_mfma_f32_16x16x32_bf16 v[68:71], v[166:169], v[206:209], v[68:71]
	v_mfma_f32_16x16x32_bf16 v[64:67], v[174:177], v[206:209], v[64:67]
	v_mfma_f32_16x16x32_bf16 v[112:115], v[170:173], v[186:189], v[112:115]
	v_mfma_f32_16x16x32_bf16 v[104:107], v[178:181], v[186:189], v[104:107]
	v_mfma_f32_16x16x32_bf16 v[96:99], v[170:173], v[194:197], v[96:99]
	v_mfma_f32_16x16x32_bf16 v[88:91], v[178:181], v[194:197], v[88:91]
	v_mfma_f32_16x16x32_bf16 v[80:83], v[170:173], v[202:205], v[80:83]
	v_mfma_f32_16x16x32_bf16 v[72:75], v[178:181], v[202:205], v[72:75]
	v_mfma_f32_16x16x32_bf16 v[68:71], v[170:173], v[210:213], v[68:71]
	v_mfma_f32_16x16x32_bf16 v[64:67], v[178:181], v[210:213], v[64:67]
	s_setprio 0
	s_barrier
; #define PG8_STAGE(bufoff, gbase, voff) do { _Pragma("unroll") for (int _i = 0; _i < 2; ++_i) \
;         __builtin_amdgcn_global_load_lds((const unsigned*)((const char*)(gbase) + (voff)[_i]), (PG8_LAS unsigned*)(lds + (bufoff) + ldsw + _i * 8192), 16, 0, 0); } while (0)
; #define PG8_LDA(dst, b, h) do { _Pragma("unroll") for (int m = 0; m < 4; ++m) _Pragma("unroll") for (int k = 0; k < 2; ++k) dst[m][k] = *(const PG8_LAS bf16x8*)(lds + PG8_SA(b, h) + aoff + m * 2048 + k * 1024); } while (0)
; #define PG8_MMA(ai, bj, At, Bt) do { __builtin_amdgcn_s_setprio(1); _Pragma("unroll") for (int m = 0; m < 4; ++m) _Pragma("unroll") for (int n = 0; n < 2; ++n) _Pragma("unroll") for (int k = 0; k < 2; ++k) \
;         acc[ai][bj][m][n] = __builtin_amdgcn_mfma_f32_16x16x32_bf16(Bt[n][k], At[m][k], acc[ai][bj][m][n], 0, 0, 0); __builtin_amdgcn_s_setprio(0); } while (0)
; #define PG8_WAIT_V(n) asm volatile("s_waitcnt vmcnt(" #n ")" ::: "memory")
; #define PG8_WAIT_L(n) asm volatile("s_waitcnt lgkmcnt(" #n ")" ::: "memory")
; #define PG8_BAR __builtin_amdgcn_s_barrier()
; #define PG8_SCHED __builtin_amdgcn_sched_barrier(0)
; template <class Epi, class Sched, bool ALIGN_EPI = false, bool SP2 = false>
; __device__ __forceinline__ void gemm_phase(PG8_LAS unsigned char* lds, const Gemm g, const Sched& S, const Epi& E, const int wid) {
;     ...
;             PG8_LDA(At, 1, 1); PG8_STAGE(PG8_SB(1, 0), b3, voffB); PG8_STAGE(PG8_SB(1, 1), b3 + hstep, voffB); PG8_STAGE(PG8_SA(1, 0), a3, voffA);
;             PG8_WAIT_V(8); PG8_WAIT_L(0); PG8_BAR; PG8_MMA(1, 0, At, B0); PG8_MMA(1, 1, At, B1); PG8_BAR; PG8_SCHED;
	s_add_i32 s28, s57, s34
	v_lshl_add_u64 v[214:215], v[214:215], 0, s[10:11]
	s_mov_b32 m0, s28
	ds_read_b128 v[182:185], v153 offset:49152
	ds_read_b128 v[186:189], v153 offset:50176
	ds_read_b128 v[190:193], v153 offset:51200
	ds_read_b128 v[194:197], v153 offset:52224
	ds_read_b128 v[198:201], v153 offset:53248
	ds_read_b128 v[202:205], v153 offset:54272
	ds_read_b128 v[206:209], v153 offset:55296
	ds_read_b128 v[210:213], v153 offset:56320
	global_load_lds_dwordx4 v[214:215], off
	s_add_i32 m0, s28, 0x2000
	s_add_u32 s26, s26, 0x40080
	v_lshl_add_u64 v[214:215], v[216:217], 0, s[10:11]
	s_addc_u32 s27, s27, 0
	s_add_i32 s28, s58, s34
	global_load_lds_dwordx4 v[214:215], off
	s_mov_b32 m0, s28
	s_nop 0
	global_load_lds_dwordx4 v132, s[26:27]
	s_add_i32 m0, s28, 0x2000
	s_nop 0
	global_load_lds_dwordx4 v128, s[26:27]
	v_lshl_add_u64 v[214:215], v[218:219], 0, s[10:11]
	s_mov_b32 m0, s44
	s_nop 0
	global_load_lds_dwordx4 v[214:215], off
	v_lshl_add_u64 v[214:215], v[220:221], 0, s[10:11]
	s_mov_b32 m0, s45
	s_nop 0
	global_load_lds_dwordx4 v[214:215], off
	s_waitcnt vmcnt(8)
	s_waitcnt lgkmcnt(0)
	s_barrier
	s_setprio 1
	s_waitcnt lgkmcnt(0)
	v_mfma_f32_16x16x32_bf16 v[60:63], v[144:147], v[182:185], v[60:63]
	v_mfma_f32_16x16x32_bf16 v[56:59], v[158:161], v[182:185], v[56:59]
	v_mfma_f32_16x16x32_bf16 v[52:55], v[144:147], v[190:193], v[52:55]
	v_mfma_f32_16x16x32_bf16 v[44:47], v[158:161], v[190:193], v[44:47]
	v_mfma_f32_16x16x32_bf16 v[36:39], v[144:147], v[198:201], v[36:39]
	v_mfma_f32_16x16x32_bf16 v[28:31], v[158:161], v[198:201], v[28:31]
	v_mfma_f32_16x16x32_bf16 v[20:23], v[144:147], v[206:209], v[20:23]
	v_mfma_f32_16x16x32_bf16 v[12:15], v[158:161], v[206:209], v[12:15]
	v_mfma_f32_16x16x32_bf16 v[60:63], v[154:157], v[186:189], v[60:63]
	v_mfma_f32_16x16x32_bf16 v[56:59], v[162:165], v[186:189], v[56:59]
	v_mfma_f32_16x16x32_bf16 v[52:55], v[154:157], v[194:197], v[52:55]
	v_mfma_f32_16x16x32_bf16 v[44:47], v[162:165], v[194:197], v[44:47]
	v_mfma_f32_16x16x32_bf16 v[36:39], v[154:157], v[202:205], v[36:39]
	v_mfma_f32_16x16x32_bf16 v[28:31], v[162:165], v[202:205], v[28:31]
	v_mfma_f32_16x16x32_bf16 v[20:23], v[154:157], v[210:213], v[20:23]
	v_mfma_f32_16x16x32_bf16 v[12:15], v[162:165], v[210:213], v[12:15]
	s_setprio 0
	s_setprio 1
	v_mfma_f32_16x16x32_bf16 v[48:51], v[166:169], v[182:185], v[48:51]
	v_mfma_f32_16x16x32_bf16 v[40:43], v[174:177], v[182:185], v[40:43]
	v_mfma_f32_16x16x32_bf16 v[32:35], v[166:169], v[190:193], v[32:35]
	v_mfma_f32_16x16x32_bf16 v[24:27], v[174:177], v[190:193], v[24:27]
	v_mfma_f32_16x16x32_bf16 v[16:19], v[166:169], v[198:201], v[16:19]
	v_mfma_f32_16x16x32_bf16 v[8:11], v[174:177], v[198:201], v[8:11]
	v_mfma_f32_16x16x32_bf16 v[4:7], v[166:169], v[206:209], v[4:7]
	v_mfma_f32_16x16x32_bf16 v[0:3], v[174:177], v[206:209], v[0:3]
	v_mfma_f32_16x16x32_bf16 v[48:51], v[170:173], v[186:189], v[48:51]
	v_mfma_f32_16x16x32_bf16 v[40:43], v[178:181], v[186:189], v[40:43]
	v_mfma_f32_16x16x32_bf16 v[32:35], v[170:173], v[194:197], v[32:35]
	v_mfma_f32_16x16x32_bf16 v[24:27], v[178:181], v[194:197], v[24:27]
	v_mfma_f32_16x16x32_bf16 v[16:19], v[170:173], v[202:205], v[16:19]
	v_mfma_f32_16x16x32_bf16 v[8:11], v[178:181], v[202:205], v[8:11]
	v_mfma_f32_16x16x32_bf16 v[4:7], v[170:173], v[210:213], v[4:7]
	v_mfma_f32_16x16x32_bf16 v[0:3], v[178:181], v[210:213], v[0:3]
	s_setprio 0
	s_barrier
	s_add_i32 s56, s56, 2
	s_add_u32 s24, s24, 0x100
	s_addc_u32 s25, s25, 0
	s_add_u32 s54, s54, 0x100
	s_addc_u32 s55, s55, 0
	s_cmp_gt_u32 s56, 13
	s_cbranch_scc0 .LBB0_204
	s_and_b64 vcc, exec, s[12:13]
	s_cbranch_vccz .LBB0_207
	s_barrier

; #define PG8_STAGE(bufoff, gbase, voff) do { _Pragma("unroll") for (int _i = 0; _i < 2; ++_i) \
;         __builtin_amdgcn_global_load_lds((const unsigned*)((const char*)(gbase) + (voff)[_i]), (PG8_LAS unsigned*)(lds + (bufoff) + ldsw + _i * 8192), 16, 0, 0); } while (0)
; #define PG8_LDA(dst, b, h) do { _Pragma("unroll") for (int m = 0; m < 4; ++m) _Pragma("unroll") for (int k = 0; k < 2; ++k) dst[m][k] = *(const PG8_LAS bf16x8*)(lds + PG8_SA(b, h) + aoff + m * 2048 + k * 1024); } while (0)
; #define PG8_LDB(dst, b, h) do { _Pragma("unroll") for (int n = 0; n < 2; ++n) _Pragma("unroll") for (int k = 0; k < 2; ++k) dst[n][k] = *(const PG8_LAS bf16x8*)(lds + PG8_SB(b, h) + boff + n * 2048 + k * 1024); } while (0)
; #define PG8_MMA(ai, bj, At, Bt) do { __builtin_amdgcn_s_setprio(1); _Pragma("unroll") for (int m = 0; m < 4; ++m) _Pragma("unroll") for (int n = 0; n < 2; ++n) _Pragma("unroll") for (int k = 0; k < 2; ++k) \
;         acc[ai][bj][m][n] = __builtin_amdgcn_mfma_f32_16x16x32_bf16(Bt[n][k], At[m][k], acc[ai][bj][m][n], 0, 0, 0); __builtin_amdgcn_s_setprio(0); } while (0)
; #define PG8_WAIT_V(n) asm volatile("s_waitcnt vmcnt(" #n ")" ::: "memory")
; #define PG8_BAR __builtin_amdgcn_s_barrier()
; template <class Epi, class Sched, bool ALIGN_EPI = false, bool SP2 = false>
; __device__ __forceinline__ void gemm_phase(PG8_LAS unsigned char* lds, const Gemm g, const Sched& S, const Epi& E, const int wid) {
;     ...
;         for (int t = 0; t < nt; t += 2) {
;             const bool last = (t == nt - 2);
;             const char* a1 = cA + (size_t)(t + 1) * kstep;
;             const char* a2 = last ? nA : cA + (size_t)(t + 2) * kstep; const char* b2 = last ? nB : cB + (size_t)(t + 2) * kstep;
;             const char* a3 = a2 + kstep; const char* b3 = b2 + kstep;
;             if (last && has_next) S.a_ready(nxt);
;             if constexpr (SP2) {
;             PG8_LDB(B0, 0, 0); PG8_LDB(B1, 0, 1); PG8_SCHED; PG8_LDA(At, 0, 0); PG8_STAGE(PG8_SA(1, 1), a1 + hstep, voffA);
;             PG8_WAIT_V(8); PG8_WAIT_L(0); PG8_BAR; PG8_MMA(0, 0, At, B0); PG8_MMA(0, 1, At, B1); PG8_BAR; PG8_SCHED;
;             PG8_LDA(At, 0, 1); PG8_STAGE(PG8_SB(0, 0), b2, voffB); PG8_STAGE(PG8_SB(0, 1), b2 + hstep, voffB); PG8_STAGE(PG8_SA(0, 0), a2, voffA);
;             PG8_WAIT_V(8); PG8_WAIT_L(0); PG8_BAR; PG8_MMA(1, 0, At, B0); PG8_MMA(1, 1, At, B1); PG8_BAR; PG8_SCHED;
.LBB0_228:
	ds_read_b128 v[152:155], v149
	ds_read_b128 v[156:159], v149 offset:1024
	ds_read_b128 v[160:163], v149 offset:2048
	ds_read_b128 v[164:167], v149 offset:3072
	ds_read_b128 v[168:171], v150
	ds_read_b128 v[172:175], v150 offset:1024
	ds_read_b128 v[176:179], v150 offset:2048
	ds_read_b128 v[180:183], v150 offset:3072
	s_add_u32 s28, s26, 0xfffc0080
	s_addc_u32 s29, s27, -1
	s_cmp_eq_u32 s55, 12
	s_cselect_b32 s31, s19, s29
	s_cselect_b32 s30, s51, s28
	s_cselect_b32 s29, s17, s54
	s_cselect_b32 s28, s52, s53
	s_add_i32 m0, s25, 0xc000
	ds_read_b128 v[184:187], v151
	ds_read_b128 v[188:191], v151 offset:1024
	ds_read_b128 v[192:195], v151 offset:2048
	ds_read_b128 v[196:199], v151 offset:3072
	ds_read_b128 v[200:203], v151 offset:4096
	ds_read_b128 v[204:207], v151 offset:5120
	ds_read_b128 v[208:211], v151 offset:6144
	ds_read_b128 v[212:215], v151 offset:7168
	global_load_lds_dwordx4 v136, s[26:27]
	s_add_i32 m0, s25, 0xe000
	s_nop 0
	global_load_lds_dwordx4 v138, s[26:27]
	s_waitcnt vmcnt(8)
	s_waitcnt lgkmcnt(0)
	s_barrier
	s_setprio 1
	s_waitcnt lgkmcnt(0)
	v_mfma_f32_16x16x32_bf16 v[124:127], v[152:155], v[184:187], v[124:127]
	v_mfma_f32_16x16x32_bf16 v[120:123], v[160:163], v[184:187], v[120:123]
	v_mfma_f32_16x16x32_bf16 v[116:119], v[152:155], v[192:195], v[116:119]
	v_mfma_f32_16x16x32_bf16 v[108:111], v[160:163], v[192:195], v[108:111]
	v_mfma_f32_16x16x32_bf16 v[100:103], v[152:155], v[200:203], v[100:103]
	v_mfma_f32_16x16x32_bf16 v[92:95], v[160:163], v[200:203], v[92:95]
	v_mfma_f32_16x16x32_bf16 v[84:87], v[152:155], v[208:211], v[84:87]
	v_mfma_f32_16x16x32_bf16 v[76:79], v[160:163], v[208:211], v[76:79]
	v_mfma_f32_16x16x32_bf16 v[124:127], v[156:159], v[188:191], v[124:127]
	v_mfma_f32_16x16x32_bf16 v[120:123], v[164:167], v[188:191], v[120:123]
	v_mfma_f32_16x16x32_bf16 v[116:119], v[156:159], v[196:199], v[116:119]
	v_mfma_f32_16x16x32_bf16 v[108:111], v[164:167], v[196:199], v[108:111]
	v_mfma_f32_16x16x32_bf16 v[100:103], v[156:159], v[204:207], v[100:103]
	v_mfma_f32_16x16x32_bf16 v[92:95], v[164:167], v[204:207], v[92:95]
	v_mfma_f32_16x16x32_bf16 v[84:87], v[156:159], v[212:215], v[84:87]
	v_mfma_f32_16x16x32_bf16 v[76:79], v[164:167], v[212:215], v[76:79]
	s_setprio 0
	s_setprio 1
	v_mfma_f32_16x16x32_bf16 v[112:115], v[168:171], v[184:187], v[112:115]
	v_mfma_f32_16x16x32_bf16 v[104:107], v[176:179], v[184:187], v[104:107]
	v_mfma_f32_16x16x32_bf16 v[96:99], v[168:171], v[192:195], v[96:99]
	v_mfma_f32_16x16x32_bf16 v[88:91], v[176:179], v[192:195], v[88:91]
	v_mfma_f32_16x16x32_bf16 v[80:83], v[168:171], v[200:203], v[80:83]
	v_mfma_f32_16x16x32_bf16 v[72:75], v[176:179], v[200:203], v[72:75]
	v_mfma_f32_16x16x32_bf16 v[68:71], v[168:171], v[208:211], v[68:71]
	v_mfma_f32_16x16x32_bf16 v[64:67], v[176:179], v[208:211], v[64:67]
	v_mfma_f32_16x16x32_bf16 v[112:115], v[172:175], v[188:191], v[112:115]
	v_mfma_f32_16x16x32_bf16 v[104:107], v[180:183], v[188:191], v[104:107]
	v_mfma_f32_16x16x32_bf16 v[96:99], v[172:175], v[196:199], v[96:99]
	v_mfma_f32_16x16x32_bf16 v[88:91], v[180:183], v[196:199], v[88:91]
	v_mfma_f32_16x16x32_bf16 v[80:83], v[172:175], v[204:207], v[80:83]
	v_mfma_f32_16x16x32_bf16 v[72:75], v[180:183], v[204:207], v[72:75]
	v_mfma_f32_16x16x32_bf16 v[68:71], v[172:175], v[212:215], v[68:71]
	v_mfma_f32_16x16x32_bf16 v[64:67], v[180:183], v[212:215], v[64:67]
	s_setprio 0
	s_barrier
	s_add_i32 s56, s36, s34
	v_lshl_add_u64 v[144:145], s[28:29], 0, v[130:131]
	s_mov_b32 m0, s56
	ds_read_b128 v[184:187], v151 offset:16384
	ds_read_b128 v[188:191], v151 offset:17408
	ds_read_b128 v[192:195], v151 offset:18432
	ds_read_b128 v[196:199], v151 offset:19456
	ds_read_b128 v[200:203], v151 offset:20480
	ds_read_b128 v[204:207], v151 offset:21504
	ds_read_b128 v[208:211], v151 offset:22528
	ds_read_b128 v[212:215], v151 offset:23552
	global_load_lds_dwordx4 v[144:145], off
	s_add_i32 m0, s56, 0x2000
	s_add_u32 s56, s28, 0x40000
	v_lshl_add_u64 v[216:217], s[28:29], 0, v[134:135]
	s_addc_u32 s57, s29, 0
	s_add_i32 s58, s46, s34
	global_load_lds_dwordx4 v[216:217], off
	s_mov_b32 m0, s58
	v_lshl_add_u64 v[220:221], s[30:31], 0, v[132:133]
	global_load_lds_dwordx4 v130, s[56:57]
	s_add_i32 m0, s58, 0x2000
	s_nop 0
	global_load_lds_dwordx4 v134, s[56:57]
	v_lshl_add_u64 v[218:219], s[30:31], 0, v[128:129]
	s_mov_b32 m0, s25
	s_nop 0
	global_load_lds_dwordx4 v[218:219], off
	s_mov_b32 m0, s41
	s_nop 0
	global_load_lds_dwordx4 v[220:221], off
	s_waitcnt vmcnt(8)
	s_waitcnt lgkmcnt(0)
	s_barrier
; #define PG8_STAGE(bufoff, gbase, voff) do { _Pragma("unroll") for (int _i = 0; _i < 2; ++_i) \
;         __builtin_amdgcn_global_load_lds((const unsigned*)((const char*)(gbase) + (voff)[_i]), (PG8_LAS unsigned*)(lds + (bufoff) + ldsw + _i * 8192), 16, 0, 0); } while (0)
; #define PG8_LDA(dst, b, h) do { _Pragma("unroll") for (int m = 0; m < 4; ++m) _Pragma("unroll") for (int k = 0; k < 2; ++k) dst[m][k] = *(const PG8_LAS bf16x8*)(lds + PG8_SA(b, h) + aoff + m * 2048 + k * 1024); } while (0)
; #define PG8_LDB(dst, b, h) do { _Pragma("unroll") for (int n = 0; n < 2; ++n) _Pragma("unroll") for (int k = 0; k < 2; ++k) dst[n][k] = *(const PG8_LAS bf16x8*)(lds + PG8_SB(b, h) + boff + n * 2048 + k * 1024); } while (0)
; #define PG8_MMA(ai, bj, At, Bt) do { __builtin_amdgcn_s_setprio(1); _Pragma("unroll") for (int m = 0; m < 4; ++m) _Pragma("unroll") for (int n = 0; n < 2; ++n) _Pragma("unroll") for (int k = 0; k < 2; ++k) \
;         acc[ai][bj][m][n] = __builtin_amdgcn_mfma_f32_16x16x32_bf16(Bt[n][k], At[m][k], acc[ai][bj][m][n], 0, 0, 0); __builtin_amdgcn_s_setprio(0); } while (0)
; #define PG8_WAIT_V(n) asm volatile("s_waitcnt vmcnt(" #n ")" ::: "memory")
; #define PG8_WAIT_L(n) asm volatile("s_waitcnt lgkmcnt(" #n ")" ::: "memory")
; #define PG8_BAR __builtin_amdgcn_s_barrier()
; #define PG8_SCHED __builtin_amdgcn_sched_barrier(0)
; template <class Epi, class Sched, bool ALIGN_EPI = false, bool SP2 = false>
; __device__ __forceinline__ void gemm_phase(PG8_LAS unsigned char* lds, const Gemm g, const Sched& S, const Epi& E, const int wid) {
;     ...
;             PG8_WAIT_V(8); PG8_WAIT_L(0); PG8_BAR; PG8_MMA(1, 0, At, B0); PG8_MMA(1, 1, At, B1); PG8_BAR; PG8_SCHED;
;             PG8_LDB(B0, 1, 0); PG8_LDB(B1, 1, 1); PG8_SCHED; PG8_LDA(At, 1, 0); PG8_STAGE(PG8_SA(0, 1), a2 + hstep, voffA);
;             PG8_WAIT_V(8); PG8_WAIT_L(0); PG8_BAR; PG8_MMA(0, 0, At, B0); PG8_MMA(0, 1, At, B1); PG8_BAR; PG8_SCHED;
	s_setprio 1
	s_waitcnt lgkmcnt(0)
	v_mfma_f32_16x16x32_bf16 v[60:63], v[152:155], v[184:187], v[60:63]
	v_mfma_f32_16x16x32_bf16 v[56:59], v[160:163], v[184:187], v[56:59]
	v_mfma_f32_16x16x32_bf16 v[52:55], v[152:155], v[192:195], v[52:55]
	v_mfma_f32_16x16x32_bf16 v[44:47], v[160:163], v[192:195], v[44:47]
	v_mfma_f32_16x16x32_bf16 v[36:39], v[152:155], v[200:203], v[36:39]
	v_mfma_f32_16x16x32_bf16 v[28:31], v[160:163], v[200:203], v[28:31]
	v_mfma_f32_16x16x32_bf16 v[20:23], v[152:155], v[208:211], v[20:23]
	v_mfma_f32_16x16x32_bf16 v[12:15], v[160:163], v[208:211], v[12:15]
	v_mfma_f32_16x16x32_bf16 v[60:63], v[156:159], v[188:191], v[60:63]
	v_mfma_f32_16x16x32_bf16 v[56:59], v[164:167], v[188:191], v[56:59]
	v_mfma_f32_16x16x32_bf16 v[52:55], v[156:159], v[196:199], v[52:55]
	v_mfma_f32_16x16x32_bf16 v[44:47], v[164:167], v[196:199], v[44:47]
	v_mfma_f32_16x16x32_bf16 v[36:39], v[156:159], v[204:207], v[36:39]
	v_mfma_f32_16x16x32_bf16 v[28:31], v[164:167], v[204:207], v[28:31]
	v_mfma_f32_16x16x32_bf16 v[20:23], v[156:159], v[212:215], v[20:23]
	v_mfma_f32_16x16x32_bf16 v[12:15], v[164:167], v[212:215], v[12:15]
	s_setprio 0
	s_setprio 1
	v_mfma_f32_16x16x32_bf16 v[48:51], v[168:171], v[184:187], v[48:51]
	v_mfma_f32_16x16x32_bf16 v[40:43], v[176:179], v[184:187], v[40:43]
	v_mfma_f32_16x16x32_bf16 v[32:35], v[168:171], v[192:195], v[32:35]
	v_mfma_f32_16x16x32_bf16 v[24:27], v[176:179], v[192:195], v[24:27]
	v_mfma_f32_16x16x32_bf16 v[16:19], v[168:171], v[200:203], v[16:19]
	v_mfma_f32_16x16x32_bf16 v[8:11], v[176:179], v[200:203], v[8:11]
	v_mfma_f32_16x16x32_bf16 v[4:7], v[168:171], v[208:211], v[4:7]
	v_mfma_f32_16x16x32_bf16 v[0:3], v[176:179], v[208:211], v[0:3]
	v_mfma_f32_16x16x32_bf16 v[48:51], v[172:175], v[188:191], v[48:51]
	v_mfma_f32_16x16x32_bf16 v[40:43], v[180:183], v[188:191], v[40:43]
	v_mfma_f32_16x16x32_bf16 v[32:35], v[172:175], v[196:199], v[32:35]
	v_mfma_f32_16x16x32_bf16 v[24:27], v[180:183], v[196:199], v[24:27]
	v_mfma_f32_16x16x32_bf16 v[16:19], v[172:175], v[204:207], v[16:19]
	v_mfma_f32_16x16x32_bf16 v[8:11], v[180:183], v[204:207], v[8:11]
	v_mfma_f32_16x16x32_bf16 v[4:7], v[172:175], v[212:215], v[4:7]
	v_mfma_f32_16x16x32_bf16 v[0:3], v[180:183], v[212:215], v[0:3]
	s_setprio 0
	s_barrier
	s_add_i32 s56, 0, 0x18000
	s_add_i32 s57, 0, 0x1c000
	v_add_u32_e32 v164, s56, v147
	v_add_u32_e32 v180, s57, v147
	ds_read_b128 v[152:155], v164
	ds_read_b128 v[156:159], v164 offset:1024
	ds_read_b128 v[160:163], v164 offset:2048
	ds_read_b128 v[164:167], v164 offset:3072
	ds_read_b128 v[168:171], v180
	ds_read_b128 v[172:175], v180 offset:1024
	ds_read_b128 v[176:179], v180 offset:2048
	ds_read_b128 v[180:183], v180 offset:3072
	s_add_u32 s30, s30, 0x40000
	s_addc_u32 s31, s31, 0
	s_mov_b32 m0, s42
	ds_read_b128 v[184:187], v151 offset:32768
	ds_read_b128 v[188:191], v151 offset:33792
	ds_read_b128 v[192:195], v151 offset:34816
	ds_read_b128 v[196:199], v151 offset:35840
	ds_read_b128 v[200:203], v151 offset:36864
	ds_read_b128 v[204:207], v151 offset:37888
	ds_read_b128 v[208:211], v151 offset:38912
	ds_read_b128 v[212:215], v151 offset:39936
	global_load_lds_dwordx4 v128, s[30:31]
	s_mov_b32 m0, s43
	s_nop 0
	global_load_lds_dwordx4 v132, s[30:31]
	s_waitcnt vmcnt(8)
	s_waitcnt lgkmcnt(0)
	s_barrier
	s_setprio 1
	s_waitcnt lgkmcnt(0)
	v_mfma_f32_16x16x32_bf16 v[124:127], v[152:155], v[184:187], v[124:127]
	v_mfma_f32_16x16x32_bf16 v[120:123], v[160:163], v[184:187], v[120:123]
	v_mfma_f32_16x16x32_bf16 v[116:119], v[152:155], v[192:195], v[116:119]
	v_mfma_f32_16x16x32_bf16 v[108:111], v[160:163], v[192:195], v[108:111]
	v_mfma_f32_16x16x32_bf16 v[100:103], v[152:155], v[200:203], v[100:103]
	v_mfma_f32_16x16x32_bf16 v[92:95], v[160:163], v[200:203], v[92:95]
	v_mfma_f32_16x16x32_bf16 v[84:87], v[152:155], v[208:211], v[84:87]
	v_mfma_f32_16x16x32_bf16 v[76:79], v[160:163], v[208:211], v[76:79]
	v_mfma_f32_16x16x32_bf16 v[124:127], v[156:159], v[188:191], v[124:127]
	v_mfma_f32_16x16x32_bf16 v[120:123], v[164:167], v[188:191], v[120:123]
	v_mfma_f32_16x16x32_bf16 v[116:119], v[156:159], v[196:199], v[116:119]
	v_mfma_f32_16x16x32_bf16 v[108:111], v[164:167], v[196:199], v[108:111]
	v_mfma_f32_16x16x32_bf16 v[100:103], v[156:159], v[204:207], v[100:103]
	v_mfma_f32_16x16x32_bf16 v[92:95], v[164:167], v[204:207], v[92:95]
	v_mfma_f32_16x16x32_bf16 v[84:87], v[156:159], v[212:215], v[84:87]
	v_mfma_f32_16x16x32_bf16 v[76:79], v[164:167], v[212:215], v[76:79]
	s_setprio 0
	s_setprio 1
	v_mfma_f32_16x16x32_bf16 v[112:115], v[168:171], v[184:187], v[112:115]
	v_mfma_f32_16x16x32_bf16 v[104:107], v[176:179], v[184:187], v[104:107]
	v_mfma_f32_16x16x32_bf16 v[96:99], v[168:171], v[192:195], v[96:99]
	v_mfma_f32_16x16x32_bf16 v[88:91], v[176:179], v[192:195], v[88:91]
	v_mfma_f32_16x16x32_bf16 v[80:83], v[168:171], v[200:203], v[80:83]
	v_mfma_f32_16x16x32_bf16 v[72:75], v[176:179], v[200:203], v[72:75]
	v_mfma_f32_16x16x32_bf16 v[68:71], v[168:171], v[208:211], v[68:71]
	v_mfma_f32_16x16x32_bf16 v[64:67], v[176:179], v[208:211], v[64:67]
	v_mfma_f32_16x16x32_bf16 v[112:115], v[172:175], v[188:191], v[112:115]
	v_mfma_f32_16x16x32_bf16 v[104:107], v[180:183], v[188:191], v[104:107]
	v_mfma_f32_16x16x32_bf16 v[96:99], v[172:175], v[196:199], v[96:99]
	v_mfma_f32_16x16x32_bf16 v[88:91], v[180:183], v[196:199], v[88:91]
	v_mfma_f32_16x16x32_bf16 v[80:83], v[172:175], v[204:207], v[80:83]
	v_mfma_f32_16x16x32_bf16 v[72:75], v[180:183], v[204:207], v[72:75]
	v_mfma_f32_16x16x32_bf16 v[68:71], v[172:175], v[212:215], v[68:71]
	v_mfma_f32_16x16x32_bf16 v[64:67], v[180:183], v[212:215], v[64:67]
	s_setprio 0
	s_barrier
; #define PG8_STAGE(bufoff, gbase, voff) do { _Pragma("unroll") for (int _i = 0; _i < 2; ++_i) \
;         __builtin_amdgcn_global_load_lds((const unsigned*)((const char*)(gbase) + (voff)[_i]), (PG8_LAS unsigned*)(lds + (bufoff) + ldsw + _i * 8192), 16, 0, 0); } while (0)
; #define PG8_LDA(dst, b, h) do { _Pragma("unroll") for (int m = 0; m < 4; ++m) _Pragma("unroll") for (int k = 0; k < 2; ++k) dst[m][k] = *(const PG8_LAS bf16x8*)(lds + PG8_SA(b, h) + aoff + m * 2048 + k * 1024); } while (0)
; #define PG8_MMA(ai, bj, At, Bt) do { __builtin_amdgcn_s_setprio(1); _Pragma("unroll") for (int m = 0; m < 4; ++m) _Pragma("unroll") for (int n = 0; n < 2; ++n) _Pragma("unroll") for (int k = 0; k < 2; ++k) \
;         acc[ai][bj][m][n] = __builtin_amdgcn_mfma_f32_16x16x32_bf16(Bt[n][k], At[m][k], acc[ai][bj][m][n], 0, 0, 0); __builtin_amdgcn_s_setprio(0); } while (0)
; #define PG8_WAIT_V(n) asm volatile("s_waitcnt vmcnt(" #n ")" ::: "memory")
; #define PG8_WAIT_L(n) asm volatile("s_waitcnt lgkmcnt(" #n ")" ::: "memory")
; #define PG8_BAR __builtin_amdgcn_s_barrier()
; #define PG8_SCHED __builtin_amdgcn_sched_barrier(0)
; template <class Epi, class Sched, bool ALIGN_EPI = false, bool SP2 = false>
; __device__ __forceinline__ void gemm_phase(PG8_LAS unsigned char* lds, const Gemm g, const Sched& S, const Epi& E, const int wid) {
;     ...
;             PG8_LDA(At, 1, 1); PG8_STAGE(PG8_SB(1, 0), b3, voffB); PG8_STAGE(PG8_SB(1, 1), b3 + hstep, voffB); PG8_STAGE(PG8_SA(1, 0), a3, voffA);
;             PG8_WAIT_V(8); PG8_WAIT_L(0); PG8_BAR; PG8_MMA(1, 0, At, B0); PG8_MMA(1, 1, At, B1); PG8_BAR; PG8_SCHED;
	s_add_i32 s30, s56, s34
	v_lshl_add_u64 v[144:145], v[144:145], 0, s[8:9]
	s_mov_b32 m0, s30
	ds_read_b128 v[184:187], v151 offset:49152
	ds_read_b128 v[188:191], v151 offset:50176
	ds_read_b128 v[192:195], v151 offset:51200
	ds_read_b128 v[196:199], v151 offset:52224
	ds_read_b128 v[200:203], v151 offset:53248
	ds_read_b128 v[204:207], v151 offset:54272
	ds_read_b128 v[208:211], v151 offset:55296
	ds_read_b128 v[212:215], v151 offset:56320
	global_load_lds_dwordx4 v[144:145], off
	s_add_i32 m0, s30, 0x2000
	s_add_u32 s28, s28, 0x40080
	v_lshl_add_u64 v[144:145], v[216:217], 0, s[8:9]
	s_addc_u32 s29, s29, 0
	s_add_i32 s30, s57, s34
	global_load_lds_dwordx4 v[144:145], off
	s_mov_b32 m0, s30
	s_nop 0
	global_load_lds_dwordx4 v130, s[28:29]
	s_add_i32 m0, s30, 0x2000
	s_nop 0
	global_load_lds_dwordx4 v134, s[28:29]
	v_lshl_add_u64 v[144:145], v[218:219], 0, s[8:9]
	s_mov_b32 m0, s37
	s_nop 0
	global_load_lds_dwordx4 v[144:145], off
	v_lshl_add_u64 v[144:145], v[220:221], 0, s[8:9]
	s_mov_b32 m0, s45
	s_nop 0
	global_load_lds_dwordx4 v[144:145], off
	s_waitcnt vmcnt(8)
	s_waitcnt lgkmcnt(0)
	s_barrier
	s_setprio 1
	s_waitcnt lgkmcnt(0)
	v_mfma_f32_16x16x32_bf16 v[60:63], v[152:155], v[184:187], v[60:63]
	v_mfma_f32_16x16x32_bf16 v[56:59], v[160:163], v[184:187], v[56:59]
	v_mfma_f32_16x16x32_bf16 v[52:55], v[152:155], v[192:195], v[52:55]
	v_mfma_f32_16x16x32_bf16 v[44:47], v[160:163], v[192:195], v[44:47]
	v_mfma_f32_16x16x32_bf16 v[36:39], v[152:155], v[200:203], v[36:39]
	v_mfma_f32_16x16x32_bf16 v[28:31], v[160:163], v[200:203], v[28:31]
	v_mfma_f32_16x16x32_bf16 v[20:23], v[152:155], v[208:211], v[20:23]
	v_mfma_f32_16x16x32_bf16 v[12:15], v[160:163], v[208:211], v[12:15]
	v_mfma_f32_16x16x32_bf16 v[60:63], v[156:159], v[188:191], v[60:63]
	v_mfma_f32_16x16x32_bf16 v[56:59], v[164:167], v[188:191], v[56:59]
	v_mfma_f32_16x16x32_bf16 v[52:55], v[156:159], v[196:199], v[52:55]
	v_mfma_f32_16x16x32_bf16 v[44:47], v[164:167], v[196:199], v[44:47]
	v_mfma_f32_16x16x32_bf16 v[36:39], v[156:159], v[204:207], v[36:39]
	v_mfma_f32_16x16x32_bf16 v[28:31], v[164:167], v[204:207], v[28:31]
	v_mfma_f32_16x16x32_bf16 v[20:23], v[156:159], v[212:215], v[20:23]
	v_mfma_f32_16x16x32_bf16 v[12:15], v[164:167], v[212:215], v[12:15]
	s_setprio 0
	s_setprio 1
	v_mfma_f32_16x16x32_bf16 v[48:51], v[168:171], v[184:187], v[48:51]
	v_mfma_f32_16x16x32_bf16 v[40:43], v[176:179], v[184:187], v[40:43]
	v_mfma_f32_16x16x32_bf16 v[32:35], v[168:171], v[192:195], v[32:35]
	v_mfma_f32_16x16x32_bf16 v[24:27], v[176:179], v[192:195], v[24:27]
	v_mfma_f32_16x16x32_bf16 v[16:19], v[168:171], v[200:203], v[16:19]
	v_mfma_f32_16x16x32_bf16 v[8:11], v[176:179], v[200:203], v[8:11]
	v_mfma_f32_16x16x32_bf16 v[4:7], v[168:171], v[208:211], v[4:7]
	v_mfma_f32_16x16x32_bf16 v[0:3], v[176:179], v[208:211], v[0:3]
	v_mfma_f32_16x16x32_bf16 v[48:51], v[172:175], v[188:191], v[48:51]
	v_mfma_f32_16x16x32_bf16 v[40:43], v[180:183], v[188:191], v[40:43]
	v_mfma_f32_16x16x32_bf16 v[32:35], v[172:175], v[196:199], v[32:35]
	v_mfma_f32_16x16x32_bf16 v[24:27], v[180:183], v[196:199], v[24:27]
	v_mfma_f32_16x16x32_bf16 v[16:19], v[172:175], v[204:207], v[16:19]
	v_mfma_f32_16x16x32_bf16 v[8:11], v[180:183], v[204:207], v[8:11]
	v_mfma_f32_16x16x32_bf16 v[4:7], v[172:175], v[212:215], v[4:7]
	v_mfma_f32_16x16x32_bf16 v[0:3], v[180:183], v[212:215], v[0:3]
	s_setprio 0
	s_barrier
	s_add_i32 s55, s55, 2
	s_add_u32 s26, s26, 0x100
	s_addc_u32 s27, s27, 0
	s_add_u32 s53, s53, 0x100
	s_addc_u32 s54, s54, 0
	s_cmp_gt_u32 s55, 13
	s_cbranch_scc0 .LBB0_228
	s_and_b64 vcc, exec, s[10:11]
	s_cbranch_vccz .LBB0_231
	s_barrier

; #define PG8_STAGE(bufoff, gbase, voff) do { _Pragma("unroll") for (int _i = 0; _i < 2; ++_i) \
;         __builtin_amdgcn_global_load_lds((const unsigned*)((const char*)(gbase) + (voff)[_i]), (PG8_LAS unsigned*)(lds + (bufoff) + ldsw + _i * 8192), 16, 0, 0); } while (0)
; #define PG8_LDA(dst, b, h) do { _Pragma("unroll") for (int m = 0; m < 4; ++m) _Pragma("unroll") for (int k = 0; k < 2; ++k) dst[m][k] = *(const PG8_LAS bf16x8*)(lds + PG8_SA(b, h) + aoff + m * 2048 + k * 1024); } while (0)
; #define PG8_LDB(dst, b, h) do { _Pragma("unroll") for (int n = 0; n < 2; ++n) _Pragma("unroll") for (int k = 0; k < 2; ++k) dst[n][k] = *(const PG8_LAS bf16x8*)(lds + PG8_SB(b, h) + boff + n * 2048 + k * 1024); } while (0)
; #define PG8_MMA(ai, bj, At, Bt) do { __builtin_amdgcn_s_setprio(1); _Pragma("unroll") for (int m = 0; m < 4; ++m) _Pragma("unroll") for (int n = 0; n < 2; ++n) _Pragma("unroll") for (int k = 0; k < 2; ++k) \
;         acc[ai][bj][m][n] = __builtin_amdgcn_mfma_f32_16x16x32_bf16(Bt[n][k], At[m][k], acc[ai][bj][m][n], 0, 0, 0); __builtin_amdgcn_s_setprio(0); } while (0)
; #define PG8_WAIT_V(n) asm volatile("s_waitcnt vmcnt(" #n ")" ::: "memory")
; #define PG8_BAR __builtin_amdgcn_s_barrier()
; template <class Epi, class Sched, bool ALIGN_EPI = false, bool SP2 = false>
; __device__ __forceinline__ void gemm_phase(PG8_LAS unsigned char* lds, const Gemm g, const Sched& S, const Epi& E, const int wid) {
;     ...
;         for (int t = 0; t < nt; t += 2) {
;             const bool last = (t == nt - 2);
;             const char* a1 = cA + (size_t)(t + 1) * kstep;
;             const char* a2 = last ? nA : cA + (size_t)(t + 2) * kstep; const char* b2 = last ? nB : cB + (size_t)(t + 2) * kstep;
;             const char* a3 = a2 + kstep; const char* b3 = b2 + kstep;
;             if (last && has_next) S.a_ready(nxt);
;             if constexpr (SP2) {
;             PG8_LDB(B0, 0, 0); PG8_LDB(B1, 0, 1); PG8_SCHED; PG8_LDA(At, 0, 0); PG8_STAGE(PG8_SA(1, 1), a1 + hstep, voffA);
;             PG8_WAIT_V(8); PG8_WAIT_L(0); PG8_BAR; PG8_MMA(0, 0, At, B0); PG8_MMA(0, 1, At, B1); PG8_BAR; PG8_SCHED;
;             PG8_LDA(At, 0, 1); PG8_STAGE(PG8_SB(0, 0), b2, voffB); PG8_STAGE(PG8_SB(0, 1), b2 + hstep, voffB); PG8_STAGE(PG8_SA(0, 0), a2, voffA);
;             PG8_WAIT_V(8); PG8_WAIT_L(0); PG8_BAR; PG8_MMA(1, 0, At, B0); PG8_MMA(1, 1, At, B1); PG8_BAR; PG8_SCHED;
.LBB0_540:
	ds_read_b128 v[48:51], v157
	ds_read_b128 v[52:55], v157 offset:1024
	ds_read_b128 v[148:151], v157 offset:2048
	ds_read_b128 v[162:165], v157 offset:3072
	ds_read_b128 v[166:169], v158
	ds_read_b128 v[170:173], v158 offset:1024
	ds_read_b128 v[174:177], v158 offset:2048
	ds_read_b128 v[178:181], v158 offset:3072
	s_add_u32 s36, s34, 0xfffc0080
	s_addc_u32 s37, s35, -1
	s_cmp_eq_u32 s53, 12
	s_cselect_b32 s39, s23, s37
	s_cselect_b32 s38, s29, s36
	s_cselect_b32 s37, s21, s52
	s_cselect_b32 s36, s50, s51
	s_add_i32 m0, s31, 0xc000
	ds_read_b128 v[182:185], v159
	ds_read_b128 v[186:189], v159 offset:1024
	ds_read_b128 v[190:193], v159 offset:2048
	ds_read_b128 v[194:197], v159 offset:3072
	ds_read_b128 v[198:201], v159 offset:4096
	ds_read_b128 v[202:205], v159 offset:5120
	ds_read_b128 v[206:209], v159 offset:6144
	ds_read_b128 v[210:213], v159 offset:7168
	global_load_lds_dwordx4 v140, s[34:35]
	s_add_i32 m0, s31, 0xe000
	s_nop 0
	global_load_lds_dwordx4 v142, s[34:35]
	s_waitcnt vmcnt(8)
	s_waitcnt lgkmcnt(0)
	s_barrier
	s_setprio 1
	s_waitcnt lgkmcnt(0)
	v_mfma_f32_16x16x32_bf16 v[132:135], v[48:51], v[182:185], v[132:135]
	v_mfma_f32_16x16x32_bf16 v[128:131], v[148:151], v[182:185], v[128:131]
	v_mfma_f32_16x16x32_bf16 v[116:119], v[48:51], v[190:193], v[116:119]
	v_mfma_f32_16x16x32_bf16 v[112:115], v[148:151], v[190:193], v[112:115]
	v_mfma_f32_16x16x32_bf16 v[100:103], v[48:51], v[198:201], v[100:103]
	v_mfma_f32_16x16x32_bf16 v[96:99], v[148:151], v[198:201], v[96:99]
	v_mfma_f32_16x16x32_bf16 v[84:87], v[48:51], v[206:209], v[84:87]
	v_mfma_f32_16x16x32_bf16 v[80:83], v[148:151], v[206:209], v[80:83]
	v_mfma_f32_16x16x32_bf16 v[132:135], v[52:55], v[186:189], v[132:135]
	v_mfma_f32_16x16x32_bf16 v[128:131], v[162:165], v[186:189], v[128:131]
	v_mfma_f32_16x16x32_bf16 v[116:119], v[52:55], v[194:197], v[116:119]
	v_mfma_f32_16x16x32_bf16 v[112:115], v[162:165], v[194:197], v[112:115]
	v_mfma_f32_16x16x32_bf16 v[100:103], v[52:55], v[202:205], v[100:103]
	v_mfma_f32_16x16x32_bf16 v[96:99], v[162:165], v[202:205], v[96:99]
	v_mfma_f32_16x16x32_bf16 v[84:87], v[52:55], v[210:213], v[84:87]
	v_mfma_f32_16x16x32_bf16 v[80:83], v[162:165], v[210:213], v[80:83]
	s_setprio 0
	s_setprio 1
	v_mfma_f32_16x16x32_bf16 v[124:127], v[166:169], v[182:185], v[124:127]
	v_mfma_f32_16x16x32_bf16 v[120:123], v[174:177], v[182:185], v[120:123]
	v_mfma_f32_16x16x32_bf16 v[108:111], v[166:169], v[190:193], v[108:111]
	v_mfma_f32_16x16x32_bf16 v[104:107], v[174:177], v[190:193], v[104:107]
	v_mfma_f32_16x16x32_bf16 v[92:95], v[166:169], v[198:201], v[92:95]
	v_mfma_f32_16x16x32_bf16 v[88:91], v[174:177], v[198:201], v[88:91]
	v_mfma_f32_16x16x32_bf16 v[76:79], v[166:169], v[206:209], v[76:79]
	v_mfma_f32_16x16x32_bf16 v[72:75], v[174:177], v[206:209], v[72:75]
	v_mfma_f32_16x16x32_bf16 v[124:127], v[170:173], v[186:189], v[124:127]
	v_mfma_f32_16x16x32_bf16 v[120:123], v[178:181], v[186:189], v[120:123]
	v_mfma_f32_16x16x32_bf16 v[108:111], v[170:173], v[194:197], v[108:111]
	v_mfma_f32_16x16x32_bf16 v[104:107], v[178:181], v[194:197], v[104:107]
	v_mfma_f32_16x16x32_bf16 v[92:95], v[170:173], v[202:205], v[92:95]
	v_mfma_f32_16x16x32_bf16 v[88:91], v[178:181], v[202:205], v[88:91]
	v_mfma_f32_16x16x32_bf16 v[76:79], v[170:173], v[210:213], v[76:79]
	v_mfma_f32_16x16x32_bf16 v[72:75], v[178:181], v[210:213], v[72:75]
	s_setprio 0
	s_barrier
	s_add_i32 s54, s48, s33
	v_lshl_add_u64 v[152:153], s[36:37], 0, v[136:137]
	s_mov_b32 m0, s54
	ds_read_b128 v[182:185], v159 offset:16384
	ds_read_b128 v[186:189], v159 offset:17408
	ds_read_b128 v[190:193], v159 offset:18432
	ds_read_b128 v[194:197], v159 offset:19456
	ds_read_b128 v[198:201], v159 offset:20480
	ds_read_b128 v[202:205], v159 offset:21504
	ds_read_b128 v[206:209], v159 offset:22528
	ds_read_b128 v[210:213], v159 offset:23552
	global_load_lds_dwordx4 v[152:153], off
	s_add_i32 m0, s54, 0x2000
	s_add_u32 s54, s36, 0x40000
	v_lshl_add_u64 v[214:215], s[36:37], 0, v[138:139]
	s_addc_u32 s55, s37, 0
	s_add_i32 s56, s49, s33
	global_load_lds_dwordx4 v[214:215], off
	s_mov_b32 m0, s56
	v_lshl_add_u64 v[218:219], s[38:39], 0, v[138:139]
	global_load_lds_dwordx4 v136, s[54:55]
	s_add_i32 m0, s56, 0x2000
	s_nop 0
	global_load_lds_dwordx4 v138, s[54:55]
	v_lshl_add_u64 v[216:217], s[38:39], 0, v[136:137]
	s_mov_b32 m0, s31
	s_nop 0
	global_load_lds_dwordx4 v[216:217], off
	s_mov_b32 m0, s40
	s_nop 0
	global_load_lds_dwordx4 v[218:219], off
	s_waitcnt vmcnt(8)
	s_waitcnt lgkmcnt(0)
	s_barrier
; #define PG8_STAGE(bufoff, gbase, voff) do { _Pragma("unroll") for (int _i = 0; _i < 2; ++_i) \
;         __builtin_amdgcn_global_load_lds((const unsigned*)((const char*)(gbase) + (voff)[_i]), (PG8_LAS unsigned*)(lds + (bufoff) + ldsw + _i * 8192), 16, 0, 0); } while (0)
; #define PG8_LDA(dst, b, h) do { _Pragma("unroll") for (int m = 0; m < 4; ++m) _Pragma("unroll") for (int k = 0; k < 2; ++k) dst[m][k] = *(const PG8_LAS bf16x8*)(lds + PG8_SA(b, h) + aoff + m * 2048 + k * 1024); } while (0)
; #define PG8_LDB(dst, b, h) do { _Pragma("unroll") for (int n = 0; n < 2; ++n) _Pragma("unroll") for (int k = 0; k < 2; ++k) dst[n][k] = *(const PG8_LAS bf16x8*)(lds + PG8_SB(b, h) + boff + n * 2048 + k * 1024); } while (0)
; #define PG8_MMA(ai, bj, At, Bt) do { __builtin_amdgcn_s_setprio(1); _Pragma("unroll") for (int m = 0; m < 4; ++m) _Pragma("unroll") for (int n = 0; n < 2; ++n) _Pragma("unroll") for (int k = 0; k < 2; ++k) \
;         acc[ai][bj][m][n] = __builtin_amdgcn_mfma_f32_16x16x32_bf16(Bt[n][k], At[m][k], acc[ai][bj][m][n], 0, 0, 0); __builtin_amdgcn_s_setprio(0); } while (0)
; #define PG8_WAIT_V(n) asm volatile("s_waitcnt vmcnt(" #n ")" ::: "memory")
; #define PG8_WAIT_L(n) asm volatile("s_waitcnt lgkmcnt(" #n ")" ::: "memory")
; #define PG8_BAR __builtin_amdgcn_s_barrier()
; #define PG8_SCHED __builtin_amdgcn_sched_barrier(0)
; template <class Epi, class Sched, bool ALIGN_EPI = false, bool SP2 = false>
; __device__ __forceinline__ void gemm_phase(PG8_LAS unsigned char* lds, const Gemm g, const Sched& S, const Epi& E, const int wid) {
;     ...
;             PG8_WAIT_V(8); PG8_WAIT_L(0); PG8_BAR; PG8_MMA(1, 0, At, B0); PG8_MMA(1, 1, At, B1); PG8_BAR; PG8_SCHED;
;             PG8_LDB(B0, 1, 0); PG8_LDB(B1, 1, 1); PG8_SCHED; PG8_LDA(At, 1, 0); PG8_STAGE(PG8_SA(0, 1), a2 + hstep, voffA);
;             PG8_WAIT_V(8); PG8_WAIT_L(0); PG8_BAR; PG8_MMA(0, 0, At, B0); PG8_MMA(0, 1, At, B1); PG8_BAR; PG8_SCHED;
	s_setprio 1
	s_waitcnt lgkmcnt(0)
	v_mfma_f32_16x16x32_bf16 v[68:71], v[48:51], v[182:185], v[68:71]
	v_mfma_f32_16x16x32_bf16 v[64:67], v[148:151], v[182:185], v[64:67]
	v_mfma_f32_16x16x32_bf16 v[44:47], v[48:51], v[190:193], v[44:47]
	v_mfma_f32_16x16x32_bf16 v[40:43], v[148:151], v[190:193], v[40:43]
	v_mfma_f32_16x16x32_bf16 v[28:31], v[48:51], v[198:201], v[28:31]
	v_mfma_f32_16x16x32_bf16 v[24:27], v[148:151], v[198:201], v[24:27]
	v_mfma_f32_16x16x32_bf16 v[12:15], v[48:51], v[206:209], v[12:15]
	v_mfma_f32_16x16x32_bf16 v[8:11], v[148:151], v[206:209], v[8:11]
	v_mfma_f32_16x16x32_bf16 v[68:71], v[52:55], v[186:189], v[68:71]
	v_mfma_f32_16x16x32_bf16 v[64:67], v[162:165], v[186:189], v[64:67]
	v_mfma_f32_16x16x32_bf16 v[44:47], v[52:55], v[194:197], v[44:47]
	v_mfma_f32_16x16x32_bf16 v[40:43], v[162:165], v[194:197], v[40:43]
	v_mfma_f32_16x16x32_bf16 v[28:31], v[52:55], v[202:205], v[28:31]
	v_mfma_f32_16x16x32_bf16 v[24:27], v[162:165], v[202:205], v[24:27]
	v_mfma_f32_16x16x32_bf16 v[12:15], v[52:55], v[210:213], v[12:15]
	v_mfma_f32_16x16x32_bf16 v[8:11], v[162:165], v[210:213], v[8:11]
	s_setprio 0
	s_setprio 1
	v_mfma_f32_16x16x32_bf16 v[36:39], v[166:169], v[190:193], v[36:39]
	v_mfma_f32_16x16x32_bf16 v[32:35], v[174:177], v[190:193], v[32:35]
	v_mfma_f32_16x16x32_bf16 v[20:23], v[166:169], v[198:201], v[20:23]
	v_mfma_f32_16x16x32_bf16 v[16:19], v[174:177], v[198:201], v[16:19]
	v_mfma_f32_16x16x32_bf16 v[4:7], v[166:169], v[206:209], v[4:7]
	v_mfma_f32_16x16x32_bf16 v[0:3], v[174:177], v[206:209], v[0:3]
	v_mfma_f32_16x16x32_bf16 v[48:51], v[166:169], v[182:185], v[60:63]
	v_mfma_f32_16x16x32_bf16 v[52:55], v[174:177], v[182:185], v[56:59]
	v_mfma_f32_16x16x32_bf16 v[36:39], v[170:173], v[194:197], v[36:39]
	v_mfma_f32_16x16x32_bf16 v[32:35], v[178:181], v[194:197], v[32:35]
	v_mfma_f32_16x16x32_bf16 v[20:23], v[170:173], v[202:205], v[20:23]
	v_mfma_f32_16x16x32_bf16 v[16:19], v[178:181], v[202:205], v[16:19]
	v_mfma_f32_16x16x32_bf16 v[4:7], v[170:173], v[210:213], v[4:7]
	v_mfma_f32_16x16x32_bf16 v[0:3], v[178:181], v[210:213], v[0:3]
	v_mfma_f32_16x16x32_bf16 v[48:51], v[170:173], v[186:189], v[48:51]
	v_mfma_f32_16x16x32_bf16 v[52:55], v[178:181], v[186:189], v[52:55]
	s_setprio 0
	s_barrier
	s_add_i32 s54, 0, 0x18000
	s_add_i32 s55, 0, 0x1c000
	v_add_u32_e32 v162, s54, v154
	v_add_u32_e32 v178, s55, v154
	ds_read_b128 v[56:59], v162
	ds_read_b128 v[60:63], v162 offset:1024
	ds_read_b128 v[148:151], v162 offset:2048
	ds_read_b128 v[162:165], v162 offset:3072
	ds_read_b128 v[166:169], v178
	ds_read_b128 v[170:173], v178 offset:1024
	ds_read_b128 v[174:177], v178 offset:2048
	ds_read_b128 v[178:181], v178 offset:3072
	s_add_u32 s38, s38, 0x40000
	s_addc_u32 s39, s39, 0
	s_mov_b32 m0, s41
	ds_read_b128 v[182:185], v159 offset:32768
	ds_read_b128 v[186:189], v159 offset:33792
	ds_read_b128 v[190:193], v159 offset:34816
	ds_read_b128 v[194:197], v159 offset:35840
	ds_read_b128 v[198:201], v159 offset:36864
	ds_read_b128 v[202:205], v159 offset:37888
	ds_read_b128 v[206:209], v159 offset:38912
	ds_read_b128 v[210:213], v159 offset:39936
	global_load_lds_dwordx4 v136, s[38:39]
	s_mov_b32 m0, s42
	s_nop 0
	global_load_lds_dwordx4 v138, s[38:39]
	s_waitcnt vmcnt(8)
	s_waitcnt lgkmcnt(0)
	s_barrier
	s_setprio 1
	s_waitcnt lgkmcnt(0)
	v_mfma_f32_16x16x32_bf16 v[132:135], v[56:59], v[182:185], v[132:135]
	v_mfma_f32_16x16x32_bf16 v[128:131], v[148:151], v[182:185], v[128:131]
	v_mfma_f32_16x16x32_bf16 v[116:119], v[56:59], v[190:193], v[116:119]
	v_mfma_f32_16x16x32_bf16 v[112:115], v[148:151], v[190:193], v[112:115]
	v_mfma_f32_16x16x32_bf16 v[100:103], v[56:59], v[198:201], v[100:103]
	v_mfma_f32_16x16x32_bf16 v[96:99], v[148:151], v[198:201], v[96:99]
	v_mfma_f32_16x16x32_bf16 v[84:87], v[56:59], v[206:209], v[84:87]
	v_mfma_f32_16x16x32_bf16 v[80:83], v[148:151], v[206:209], v[80:83]
	v_mfma_f32_16x16x32_bf16 v[132:135], v[60:63], v[186:189], v[132:135]
	v_mfma_f32_16x16x32_bf16 v[128:131], v[162:165], v[186:189], v[128:131]
	v_mfma_f32_16x16x32_bf16 v[116:119], v[60:63], v[194:197], v[116:119]
	v_mfma_f32_16x16x32_bf16 v[112:115], v[162:165], v[194:197], v[112:115]
	v_mfma_f32_16x16x32_bf16 v[100:103], v[60:63], v[202:205], v[100:103]
	v_mfma_f32_16x16x32_bf16 v[96:99], v[162:165], v[202:205], v[96:99]
	v_mfma_f32_16x16x32_bf16 v[84:87], v[60:63], v[210:213], v[84:87]
	v_mfma_f32_16x16x32_bf16 v[80:83], v[162:165], v[210:213], v[80:83]
	s_setprio 0
	s_setprio 1
	v_mfma_f32_16x16x32_bf16 v[124:127], v[166:169], v[182:185], v[124:127]
	v_mfma_f32_16x16x32_bf16 v[120:123], v[174:177], v[182:185], v[120:123]
	v_mfma_f32_16x16x32_bf16 v[108:111], v[166:169], v[190:193], v[108:111]
	v_mfma_f32_16x16x32_bf16 v[104:107], v[174:177], v[190:193], v[104:107]
	v_mfma_f32_16x16x32_bf16 v[92:95], v[166:169], v[198:201], v[92:95]
	v_mfma_f32_16x16x32_bf16 v[88:91], v[174:177], v[198:201], v[88:91]
	v_mfma_f32_16x16x32_bf16 v[76:79], v[166:169], v[206:209], v[76:79]
	v_mfma_f32_16x16x32_bf16 v[72:75], v[174:177], v[206:209], v[72:75]
	v_mfma_f32_16x16x32_bf16 v[124:127], v[170:173], v[186:189], v[124:127]
	v_mfma_f32_16x16x32_bf16 v[120:123], v[178:181], v[186:189], v[120:123]
	v_mfma_f32_16x16x32_bf16 v[108:111], v[170:173], v[194:197], v[108:111]
	v_mfma_f32_16x16x32_bf16 v[104:107], v[178:181], v[194:197], v[104:107]
	v_mfma_f32_16x16x32_bf16 v[92:95], v[170:173], v[202:205], v[92:95]
	v_mfma_f32_16x16x32_bf16 v[88:91], v[178:181], v[202:205], v[88:91]
	v_mfma_f32_16x16x32_bf16 v[76:79], v[170:173], v[210:213], v[76:79]
	v_mfma_f32_16x16x32_bf16 v[72:75], v[178:181], v[210:213], v[72:75]
	s_setprio 0
	s_barrier
; #define PG8_STAGE(bufoff, gbase, voff) do { _Pragma("unroll") for (int _i = 0; _i < 2; ++_i) \
;         __builtin_amdgcn_global_load_lds((const unsigned*)((const char*)(gbase) + (voff)[_i]), (PG8_LAS unsigned*)(lds + (bufoff) + ldsw + _i * 8192), 16, 0, 0); } while (0)
; #define PG8_LDA(dst, b, h) do { _Pragma("unroll") for (int m = 0; m < 4; ++m) _Pragma("unroll") for (int k = 0; k < 2; ++k) dst[m][k] = *(const PG8_LAS bf16x8*)(lds + PG8_SA(b, h) + aoff + m * 2048 + k * 1024); } while (0)
; #define PG8_MMA(ai, bj, At, Bt) do { __builtin_amdgcn_s_setprio(1); _Pragma("unroll") for (int m = 0; m < 4; ++m) _Pragma("unroll") for (int n = 0; n < 2; ++n) _Pragma("unroll") for (int k = 0; k < 2; ++k) \
;         acc[ai][bj][m][n] = __builtin_amdgcn_mfma_f32_16x16x32_bf16(Bt[n][k], At[m][k], acc[ai][bj][m][n], 0, 0, 0); __builtin_amdgcn_s_setprio(0); } while (0)
; #define PG8_WAIT_V(n) asm volatile("s_waitcnt vmcnt(" #n ")" ::: "memory")
; #define PG8_WAIT_L(n) asm volatile("s_waitcnt lgkmcnt(" #n ")" ::: "memory")
; #define PG8_BAR __builtin_amdgcn_s_barrier()
; #define PG8_SCHED __builtin_amdgcn_sched_barrier(0)
; template <class Epi, class Sched, bool ALIGN_EPI = false, bool SP2 = false>
; __device__ __forceinline__ void gemm_phase(PG8_LAS unsigned char* lds, const Gemm g, const Sched& S, const Epi& E, const int wid) {
;     ...
;             PG8_LDA(At, 1, 1); PG8_STAGE(PG8_SB(1, 0), b3, voffB); PG8_STAGE(PG8_SB(1, 1), b3 + hstep, voffB); PG8_STAGE(PG8_SA(1, 0), a3, voffA);
;             PG8_WAIT_V(8); PG8_WAIT_L(0); PG8_BAR; PG8_MMA(1, 0, At, B0); PG8_MMA(1, 1, At, B1); PG8_BAR; PG8_SCHED;
	s_add_i32 s38, s54, s33
	v_lshl_add_u64 v[152:153], v[152:153], 0, s[14:15]
	s_mov_b32 m0, s38
	ds_read_b128 v[182:185], v159 offset:49152
	ds_read_b128 v[186:189], v159 offset:50176
	ds_read_b128 v[190:193], v159 offset:51200
	ds_read_b128 v[194:197], v159 offset:52224
	ds_read_b128 v[198:201], v159 offset:53248
	ds_read_b128 v[202:205], v159 offset:54272
	ds_read_b128 v[206:209], v159 offset:55296
	ds_read_b128 v[210:213], v159 offset:56320
	global_load_lds_dwordx4 v[152:153], off
	s_add_i32 m0, s38, 0x2000
	s_add_u32 s36, s36, 0x40080
	v_lshl_add_u64 v[152:153], v[214:215], 0, s[14:15]
	s_addc_u32 s37, s37, 0
	s_add_i32 s38, s55, s33
	global_load_lds_dwordx4 v[152:153], off
	s_mov_b32 m0, s38
	s_nop 0
	global_load_lds_dwordx4 v136, s[36:37]
	s_add_i32 m0, s38, 0x2000
	s_nop 0
	global_load_lds_dwordx4 v138, s[36:37]
	v_lshl_add_u64 v[152:153], v[216:217], 0, s[14:15]
	s_mov_b32 m0, s44
	s_nop 0
	global_load_lds_dwordx4 v[152:153], off
	v_lshl_add_u64 v[152:153], v[218:219], 0, s[14:15]
	s_mov_b32 m0, s45
	s_nop 0
	global_load_lds_dwordx4 v[152:153], off
	s_waitcnt vmcnt(8)
	s_waitcnt lgkmcnt(0)
	s_barrier
	s_setprio 1
	s_waitcnt lgkmcnt(0)
	v_mfma_f32_16x16x32_bf16 v[68:71], v[56:59], v[182:185], v[68:71]
	v_mfma_f32_16x16x32_bf16 v[64:67], v[148:151], v[182:185], v[64:67]
	v_mfma_f32_16x16x32_bf16 v[44:47], v[56:59], v[190:193], v[44:47]
	v_mfma_f32_16x16x32_bf16 v[40:43], v[148:151], v[190:193], v[40:43]
	v_mfma_f32_16x16x32_bf16 v[28:31], v[56:59], v[198:201], v[28:31]
	v_mfma_f32_16x16x32_bf16 v[24:27], v[148:151], v[198:201], v[24:27]
	v_mfma_f32_16x16x32_bf16 v[12:15], v[56:59], v[206:209], v[12:15]
	v_mfma_f32_16x16x32_bf16 v[8:11], v[148:151], v[206:209], v[8:11]
	v_mfma_f32_16x16x32_bf16 v[68:71], v[60:63], v[186:189], v[68:71]
	v_mfma_f32_16x16x32_bf16 v[64:67], v[162:165], v[186:189], v[64:67]
	v_mfma_f32_16x16x32_bf16 v[44:47], v[60:63], v[194:197], v[44:47]
	v_mfma_f32_16x16x32_bf16 v[40:43], v[162:165], v[194:197], v[40:43]
	v_mfma_f32_16x16x32_bf16 v[28:31], v[60:63], v[202:205], v[28:31]
	v_mfma_f32_16x16x32_bf16 v[24:27], v[162:165], v[202:205], v[24:27]
	v_mfma_f32_16x16x32_bf16 v[12:15], v[60:63], v[210:213], v[12:15]
	v_mfma_f32_16x16x32_bf16 v[8:11], v[162:165], v[210:213], v[8:11]
	s_setprio 0
	s_setprio 1
	v_mfma_f32_16x16x32_bf16 v[48:51], v[166:169], v[182:185], v[48:51]
	v_mfma_f32_16x16x32_bf16 v[60:63], v[170:173], v[186:189], v[48:51]
	v_mfma_f32_16x16x32_bf16 v[48:51], v[174:177], v[182:185], v[52:55]
	v_mfma_f32_16x16x32_bf16 v[36:39], v[166:169], v[190:193], v[36:39]
	v_mfma_f32_16x16x32_bf16 v[32:35], v[174:177], v[190:193], v[32:35]
	v_mfma_f32_16x16x32_bf16 v[20:23], v[166:169], v[198:201], v[20:23]
	v_mfma_f32_16x16x32_bf16 v[16:19], v[174:177], v[198:201], v[16:19]
	v_mfma_f32_16x16x32_bf16 v[4:7], v[166:169], v[206:209], v[4:7]
	v_mfma_f32_16x16x32_bf16 v[0:3], v[174:177], v[206:209], v[0:3]
	v_mfma_f32_16x16x32_bf16 v[56:59], v[178:181], v[186:189], v[48:51]
	v_mfma_f32_16x16x32_bf16 v[36:39], v[170:173], v[194:197], v[36:39]
	v_mfma_f32_16x16x32_bf16 v[32:35], v[178:181], v[194:197], v[32:35]
	v_mfma_f32_16x16x32_bf16 v[20:23], v[170:173], v[202:205], v[20:23]
	v_mfma_f32_16x16x32_bf16 v[16:19], v[178:181], v[202:205], v[16:19]
	v_mfma_f32_16x16x32_bf16 v[4:7], v[170:173], v[210:213], v[4:7]
	v_mfma_f32_16x16x32_bf16 v[0:3], v[178:181], v[210:213], v[0:3]
	s_setprio 0
	s_barrier
	s_add_i32 s53, s53, 2
	s_add_u32 s34, s34, 0x100
	s_addc_u32 s35, s35, 0
	s_add_u32 s51, s51, 0x100
	s_addc_u32 s52, s52, 0
	s_cmp_gt_u32 s53, 13
	s_cbranch_scc0 .LBB0_540
	s_and_b64 vcc, exec, s[16:17]
	s_cbranch_vccz .LBB0_543
	s_barrier

; #define PG8_STAGE(bufoff, gbase, voff) do { _Pragma("unroll") for (int _i = 0; _i < 2; ++_i) \
;         __builtin_amdgcn_global_load_lds((const unsigned*)((const char*)(gbase) + (voff)[_i]), (PG8_LAS unsigned*)(lds + (bufoff) + ldsw + _i * 8192), 16, 0, 0); } while (0)
; #define PG8_LDA(dst, b, h) do { _Pragma("unroll") for (int m = 0; m < 4; ++m) _Pragma("unroll") for (int k = 0; k < 2; ++k) dst[m][k] = *(const PG8_LAS bf16x8*)(lds + PG8_SA(b, h) + aoff + m * 2048 + k * 1024); } while (0)
; #define PG8_LDB(dst, b, h) do { _Pragma("unroll") for (int n = 0; n < 2; ++n) _Pragma("unroll") for (int k = 0; k < 2; ++k) dst[n][k] = *(const PG8_LAS bf16x8*)(lds + PG8_SB(b, h) + boff + n * 2048 + k * 1024); } while (0)
; #define PG8_MMA(ai, bj, At, Bt) do { __builtin_amdgcn_s_setprio(1); _Pragma("unroll") for (int m = 0; m < 4; ++m) _Pragma("unroll") for (int n = 0; n < 2; ++n) _Pragma("unroll") for (int k = 0; k < 2; ++k) \
;         acc[ai][bj][m][n] = __builtin_amdgcn_mfma_f32_16x16x32_bf16(Bt[n][k], At[m][k], acc[ai][bj][m][n], 0, 0, 0); __builtin_amdgcn_s_setprio(0); } while (0)
; #define PG8_WAIT_V(n) asm volatile("s_waitcnt vmcnt(" #n ")" ::: "memory")
; #define PG8_WAIT_L(n) asm volatile("s_waitcnt lgkmcnt(" #n ")" ::: "memory")
; #define PG8_BAR __builtin_amdgcn_s_barrier()
; #define PG8_SCHED __builtin_amdgcn_sched_barrier(0)
; template <class Epi, class Sched, bool ALIGN_EPI = false, bool SP2 = false>
; __device__ __forceinline__ void gemm_phase(PG8_LAS unsigned char* lds, const Gemm g, const Sched& S, const Epi& E, const int wid) {
;     ...
;             PG8_LDB(B0, 0, 0); PG8_LDB(B1, 0, 1); PG8_SCHED; PG8_LDA(At, 0, 0); PG8_STAGE(PG8_SA(1, 1), a1 + hstep, voffA);
;             PG8_WAIT_V(8); PG8_WAIT_L(0); PG8_BAR; PG8_MMA(0, 0, At, B0); PG8_MMA(0, 1, At, B1); PG8_BAR; PG8_SCHED;
;             PG8_LDA(At, 0, 1); PG8_STAGE(PG8_SB(0, 0), b2, voffB); PG8_STAGE(PG8_SB(0, 1), b2 + hstep, voffB); PG8_STAGE(PG8_SA(0, 0), a2, voffA);
;             PG8_WAIT_V(8); PG8_WAIT_L(0); PG8_BAR; PG8_MMA(1, 0, At, B0); PG8_MMA(1, 1, At, B1); PG8_BAR; PG8_SCHED;
.LBB0_629:
	ds_read_b128 v[112:115], v171
	ds_read_b128 v[116:119], v171 offset:1024
	ds_read_b128 v[120:123], v171 offset:2048
	ds_read_b128 v[124:127], v171 offset:3072
	ds_read_b128 v[160:163], v172
	ds_read_b128 v[164:167], v172 offset:1024
	ds_read_b128 v[176:179], v172 offset:2048
	ds_read_b128 v[180:183], v172 offset:3072
	s_add_u32 s24, s22, 0xfffc0080
	s_addc_u32 s25, s23, -1
	s_cmp_eq_u32 s53, 12
	s_cselect_b32 s27, s17, s25
	s_cselect_b32 s26, s49, s24
	s_cselect_b32 s25, s15, s52
	s_cselect_b32 s24, s50, s51
	s_add_i32 m0, s37, 0xc000
	ds_read_b128 v[184:187], v173
	ds_read_b128 v[188:191], v173 offset:1024
	ds_read_b128 v[192:195], v173 offset:2048
	ds_read_b128 v[196:199], v173 offset:3072
	ds_read_b128 v[200:203], v173 offset:4096
	ds_read_b128 v[204:207], v173 offset:5120
	ds_read_b128 v[208:211], v173 offset:6144
	ds_read_b128 v[212:215], v173 offset:7168
	global_load_lds_dwordx4 v152, s[22:23]
	s_add_i32 m0, s37, 0xe000
	s_nop 0
	global_load_lds_dwordx4 v154, s[22:23]
	s_waitcnt vmcnt(8)
	s_waitcnt lgkmcnt(0)
	s_barrier
	s_setprio 1
	s_waitcnt lgkmcnt(0)
	v_mfma_f32_16x16x32_bf16 v[140:143], v[112:115], v[184:187], v[140:143]
	v_mfma_f32_16x16x32_bf16 v[136:139], v[120:123], v[184:187], v[136:139]
	v_mfma_f32_16x16x32_bf16 v[108:111], v[112:115], v[192:195], v[108:111]
	v_mfma_f32_16x16x32_bf16 v[104:107], v[120:123], v[192:195], v[104:107]
	v_mfma_f32_16x16x32_bf16 v[92:95], v[112:115], v[200:203], v[92:95]
	v_mfma_f32_16x16x32_bf16 v[88:91], v[120:123], v[200:203], v[88:91]
	v_mfma_f32_16x16x32_bf16 v[76:79], v[112:115], v[208:211], v[76:79]
	v_mfma_f32_16x16x32_bf16 v[72:75], v[120:123], v[208:211], v[72:75]
	v_mfma_f32_16x16x32_bf16 v[140:143], v[116:119], v[188:191], v[140:143]
	v_mfma_f32_16x16x32_bf16 v[136:139], v[124:127], v[188:191], v[136:139]
	v_mfma_f32_16x16x32_bf16 v[108:111], v[116:119], v[196:199], v[108:111]
	v_mfma_f32_16x16x32_bf16 v[104:107], v[124:127], v[196:199], v[104:107]
	v_mfma_f32_16x16x32_bf16 v[92:95], v[116:119], v[204:207], v[92:95]
	v_mfma_f32_16x16x32_bf16 v[88:91], v[124:127], v[204:207], v[88:91]
	v_mfma_f32_16x16x32_bf16 v[76:79], v[116:119], v[212:215], v[76:79]
	v_mfma_f32_16x16x32_bf16 v[72:75], v[124:127], v[212:215], v[72:75]
	s_setprio 0
	s_setprio 1
	v_mfma_f32_16x16x32_bf16 v[132:135], v[160:163], v[184:187], v[132:135]
	v_mfma_f32_16x16x32_bf16 v[128:131], v[176:179], v[184:187], v[128:131]
	v_mfma_f32_16x16x32_bf16 v[100:103], v[160:163], v[192:195], v[100:103]
	v_mfma_f32_16x16x32_bf16 v[96:99], v[176:179], v[192:195], v[96:99]
	v_mfma_f32_16x16x32_bf16 v[84:87], v[160:163], v[200:203], v[84:87]
	v_mfma_f32_16x16x32_bf16 v[80:83], v[176:179], v[200:203], v[80:83]
	v_mfma_f32_16x16x32_bf16 v[68:71], v[160:163], v[208:211], v[68:71]
	v_mfma_f32_16x16x32_bf16 v[64:67], v[176:179], v[208:211], v[64:67]
	v_mfma_f32_16x16x32_bf16 v[132:135], v[164:167], v[188:191], v[132:135]
	v_mfma_f32_16x16x32_bf16 v[128:131], v[180:183], v[188:191], v[128:131]
	v_mfma_f32_16x16x32_bf16 v[100:103], v[164:167], v[196:199], v[100:103]
	v_mfma_f32_16x16x32_bf16 v[96:99], v[180:183], v[196:199], v[96:99]
	v_mfma_f32_16x16x32_bf16 v[84:87], v[164:167], v[204:207], v[84:87]
	v_mfma_f32_16x16x32_bf16 v[80:83], v[180:183], v[204:207], v[80:83]
	v_mfma_f32_16x16x32_bf16 v[68:71], v[164:167], v[212:215], v[68:71]
	v_mfma_f32_16x16x32_bf16 v[64:67], v[180:183], v[212:215], v[64:67]
	s_setprio 0
	s_barrier
	s_add_i32 s54, s45, s33
	v_lshl_add_u64 v[216:217], s[24:25], 0, v[148:149]
	s_mov_b32 m0, s54
	ds_read_b128 v[184:187], v173 offset:16384
	ds_read_b128 v[188:191], v173 offset:17408
	ds_read_b128 v[192:195], v173 offset:18432
	ds_read_b128 v[196:199], v173 offset:19456
	ds_read_b128 v[200:203], v173 offset:20480
	ds_read_b128 v[204:207], v173 offset:21504
	ds_read_b128 v[208:211], v173 offset:22528
	ds_read_b128 v[212:215], v173 offset:23552
	global_load_lds_dwordx4 v[216:217], off
	s_add_i32 m0, s54, 0x2000
	s_add_u32 s54, s24, 0x40000
	v_lshl_add_u64 v[218:219], s[24:25], 0, v[144:145]
	s_addc_u32 s55, s25, 0
	s_add_i32 s56, s46, s33
	global_load_lds_dwordx4 v[218:219], off
	s_mov_b32 m0, s56
	v_lshl_add_u64 v[222:223], s[26:27], 0, v[146:147]
	global_load_lds_dwordx4 v148, s[54:55]
	s_add_i32 m0, s56, 0x2000
	s_nop 0
	global_load_lds_dwordx4 v144, s[54:55]
	v_lshl_add_u64 v[220:221], s[26:27], 0, v[150:151]
	s_mov_b32 m0, s37
	s_nop 0
	global_load_lds_dwordx4 v[220:221], off
	s_mov_b32 m0, s38
	s_nop 0
	global_load_lds_dwordx4 v[222:223], off
	s_waitcnt vmcnt(8)
	s_waitcnt lgkmcnt(0)
	s_barrier
; #define PG8_STAGE(bufoff, gbase, voff) do { _Pragma("unroll") for (int _i = 0; _i < 2; ++_i) \
;         __builtin_amdgcn_global_load_lds((const unsigned*)((const char*)(gbase) + (voff)[_i]), (PG8_LAS unsigned*)(lds + (bufoff) + ldsw + _i * 8192), 16, 0, 0); } while (0)
; #define PG8_LDA(dst, b, h) do { _Pragma("unroll") for (int m = 0; m < 4; ++m) _Pragma("unroll") for (int k = 0; k < 2; ++k) dst[m][k] = *(const PG8_LAS bf16x8*)(lds + PG8_SA(b, h) + aoff + m * 2048 + k * 1024); } while (0)
; #define PG8_LDB(dst, b, h) do { _Pragma("unroll") for (int n = 0; n < 2; ++n) _Pragma("unroll") for (int k = 0; k < 2; ++k) dst[n][k] = *(const PG8_LAS bf16x8*)(lds + PG8_SB(b, h) + boff + n * 2048 + k * 1024); } while (0)
; #define PG8_MMA(ai, bj, At, Bt) do { __builtin_amdgcn_s_setprio(1); _Pragma("unroll") for (int m = 0; m < 4; ++m) _Pragma("unroll") for (int n = 0; n < 2; ++n) _Pragma("unroll") for (int k = 0; k < 2; ++k) \
;         acc[ai][bj][m][n] = __builtin_amdgcn_mfma_f32_16x16x32_bf16(Bt[n][k], At[m][k], acc[ai][bj][m][n], 0, 0, 0); __builtin_amdgcn_s_setprio(0); } while (0)
; #define PG8_WAIT_V(n) asm volatile("s_waitcnt vmcnt(" #n ")" ::: "memory")
; #define PG8_WAIT_L(n) asm volatile("s_waitcnt lgkmcnt(" #n ")" ::: "memory")
; #define PG8_BAR __builtin_amdgcn_s_barrier()
; #define PG8_SCHED __builtin_amdgcn_sched_barrier(0)
; template <class Epi, class Sched, bool ALIGN_EPI = false, bool SP2 = false>
; __device__ __forceinline__ void gemm_phase(PG8_LAS unsigned char* lds, const Gemm g, const Sched& S, const Epi& E, const int wid) {
;     ...
;             PG8_LDA(At, 0, 1); PG8_STAGE(PG8_SB(0, 0), b2, voffB); PG8_STAGE(PG8_SB(0, 1), b2 + hstep, voffB); PG8_STAGE(PG8_SA(0, 0), a2, voffA);
;             PG8_WAIT_V(8); PG8_WAIT_L(0); PG8_BAR; PG8_MMA(1, 0, At, B0); PG8_MMA(1, 1, At, B1); PG8_BAR; PG8_SCHED;
;             PG8_LDB(B0, 1, 0); PG8_LDB(B1, 1, 1); PG8_SCHED; PG8_LDA(At, 1, 0); PG8_STAGE(PG8_SA(0, 1), a2 + hstep, voffA);
;             PG8_WAIT_V(8); PG8_WAIT_L(0); PG8_BAR; PG8_MMA(0, 0, At, B0); PG8_MMA(0, 1, At, B1); PG8_BAR; PG8_SCHED;
	s_setprio 1
	s_waitcnt lgkmcnt(0)
	v_mfma_f32_16x16x32_bf16 v[60:63], v[112:115], v[184:187], v[60:63]
	v_mfma_f32_16x16x32_bf16 v[56:59], v[120:123], v[184:187], v[56:59]
	v_mfma_f32_16x16x32_bf16 v[44:47], v[112:115], v[192:195], v[44:47]
	v_mfma_f32_16x16x32_bf16 v[40:43], v[120:123], v[192:195], v[40:43]
	v_mfma_f32_16x16x32_bf16 v[28:31], v[112:115], v[200:203], v[28:31]
	v_mfma_f32_16x16x32_bf16 v[24:27], v[120:123], v[200:203], v[24:27]
	v_mfma_f32_16x16x32_bf16 v[12:15], v[112:115], v[208:211], v[12:15]
	v_mfma_f32_16x16x32_bf16 v[8:11], v[120:123], v[208:211], v[8:11]
	v_mfma_f32_16x16x32_bf16 v[60:63], v[116:119], v[188:191], v[60:63]
	v_mfma_f32_16x16x32_bf16 v[56:59], v[124:127], v[188:191], v[56:59]
	v_mfma_f32_16x16x32_bf16 v[44:47], v[116:119], v[196:199], v[44:47]
	v_mfma_f32_16x16x32_bf16 v[40:43], v[124:127], v[196:199], v[40:43]
	v_mfma_f32_16x16x32_bf16 v[28:31], v[116:119], v[204:207], v[28:31]
	v_mfma_f32_16x16x32_bf16 v[24:27], v[124:127], v[204:207], v[24:27]
	v_mfma_f32_16x16x32_bf16 v[12:15], v[116:119], v[212:215], v[12:15]
	v_mfma_f32_16x16x32_bf16 v[8:11], v[124:127], v[212:215], v[8:11]
	s_setprio 0
	s_setprio 1
	v_mfma_f32_16x16x32_bf16 v[52:55], v[160:163], v[184:187], v[52:55]
	v_mfma_f32_16x16x32_bf16 v[48:51], v[176:179], v[184:187], v[48:51]
	v_mfma_f32_16x16x32_bf16 v[36:39], v[160:163], v[192:195], v[36:39]
	v_mfma_f32_16x16x32_bf16 v[32:35], v[176:179], v[192:195], v[32:35]
	v_mfma_f32_16x16x32_bf16 v[20:23], v[160:163], v[200:203], v[20:23]
	v_mfma_f32_16x16x32_bf16 v[16:19], v[176:179], v[200:203], v[16:19]
	v_mfma_f32_16x16x32_bf16 v[4:7], v[160:163], v[208:211], v[4:7]
	v_mfma_f32_16x16x32_bf16 v[0:3], v[176:179], v[208:211], v[0:3]
	v_mfma_f32_16x16x32_bf16 v[52:55], v[164:167], v[188:191], v[52:55]
	v_mfma_f32_16x16x32_bf16 v[48:51], v[180:183], v[188:191], v[48:51]
	v_mfma_f32_16x16x32_bf16 v[36:39], v[164:167], v[196:199], v[36:39]
	v_mfma_f32_16x16x32_bf16 v[32:35], v[180:183], v[196:199], v[32:35]
	v_mfma_f32_16x16x32_bf16 v[20:23], v[164:167], v[204:207], v[20:23]
	v_mfma_f32_16x16x32_bf16 v[16:19], v[180:183], v[204:207], v[16:19]
	v_mfma_f32_16x16x32_bf16 v[4:7], v[164:167], v[212:215], v[4:7]
	v_mfma_f32_16x16x32_bf16 v[0:3], v[180:183], v[212:215], v[0:3]
	s_setprio 0
	s_barrier
	s_add_i32 s54, 0, 0x18000
	s_add_i32 s55, 0, 0x1c000
	v_add_u32_e32 v124, s54, v169
	v_add_u32_e32 v180, s55, v169
	ds_read_b128 v[112:115], v124
	ds_read_b128 v[116:119], v124 offset:1024
	ds_read_b128 v[120:123], v124 offset:2048
	ds_read_b128 v[124:127], v124 offset:3072
	ds_read_b128 v[160:163], v180
	ds_read_b128 v[164:167], v180 offset:1024
	ds_read_b128 v[176:179], v180 offset:2048
	ds_read_b128 v[180:183], v180 offset:3072
	s_add_u32 s26, s26, 0x40000
	s_addc_u32 s27, s27, 0
	s_mov_b32 m0, s39
	ds_read_b128 v[184:187], v173 offset:32768
	ds_read_b128 v[188:191], v173 offset:33792
	ds_read_b128 v[192:195], v173 offset:34816
	ds_read_b128 v[196:199], v173 offset:35840
	ds_read_b128 v[200:203], v173 offset:36864
	ds_read_b128 v[204:207], v173 offset:37888
	ds_read_b128 v[208:211], v173 offset:38912
	ds_read_b128 v[212:215], v173 offset:39936
	global_load_lds_dwordx4 v150, s[26:27]
	s_mov_b32 m0, s40
	s_nop 0
	global_load_lds_dwordx4 v146, s[26:27]
	s_waitcnt vmcnt(8)
	s_waitcnt lgkmcnt(0)
	s_barrier
	s_setprio 1
	s_waitcnt lgkmcnt(0)
	v_mfma_f32_16x16x32_bf16 v[140:143], v[112:115], v[184:187], v[140:143]
	v_mfma_f32_16x16x32_bf16 v[136:139], v[120:123], v[184:187], v[136:139]
	v_mfma_f32_16x16x32_bf16 v[108:111], v[112:115], v[192:195], v[108:111]
	v_mfma_f32_16x16x32_bf16 v[104:107], v[120:123], v[192:195], v[104:107]
	v_mfma_f32_16x16x32_bf16 v[92:95], v[112:115], v[200:203], v[92:95]
	v_mfma_f32_16x16x32_bf16 v[88:91], v[120:123], v[200:203], v[88:91]
	v_mfma_f32_16x16x32_bf16 v[76:79], v[112:115], v[208:211], v[76:79]
	v_mfma_f32_16x16x32_bf16 v[72:75], v[120:123], v[208:211], v[72:75]
	v_mfma_f32_16x16x32_bf16 v[140:143], v[116:119], v[188:191], v[140:143]
	v_mfma_f32_16x16x32_bf16 v[136:139], v[124:127], v[188:191], v[136:139]
	v_mfma_f32_16x16x32_bf16 v[108:111], v[116:119], v[196:199], v[108:111]
	v_mfma_f32_16x16x32_bf16 v[104:107], v[124:127], v[196:199], v[104:107]
	v_mfma_f32_16x16x32_bf16 v[92:95], v[116:119], v[204:207], v[92:95]
	v_mfma_f32_16x16x32_bf16 v[88:91], v[124:127], v[204:207], v[88:91]
	v_mfma_f32_16x16x32_bf16 v[76:79], v[116:119], v[212:215], v[76:79]
	v_mfma_f32_16x16x32_bf16 v[72:75], v[124:127], v[212:215], v[72:75]
	s_setprio 0
	s_setprio 1
	v_mfma_f32_16x16x32_bf16 v[132:135], v[160:163], v[184:187], v[132:135]
	v_mfma_f32_16x16x32_bf16 v[128:131], v[176:179], v[184:187], v[128:131]
	v_mfma_f32_16x16x32_bf16 v[100:103], v[160:163], v[192:195], v[100:103]
	v_mfma_f32_16x16x32_bf16 v[96:99], v[176:179], v[192:195], v[96:99]
	v_mfma_f32_16x16x32_bf16 v[84:87], v[160:163], v[200:203], v[84:87]
	v_mfma_f32_16x16x32_bf16 v[80:83], v[176:179], v[200:203], v[80:83]
	v_mfma_f32_16x16x32_bf16 v[68:71], v[160:163], v[208:211], v[68:71]
	v_mfma_f32_16x16x32_bf16 v[64:67], v[176:179], v[208:211], v[64:67]
	v_mfma_f32_16x16x32_bf16 v[132:135], v[164:167], v[188:191], v[132:135]
	v_mfma_f32_16x16x32_bf16 v[128:131], v[180:183], v[188:191], v[128:131]
	v_mfma_f32_16x16x32_bf16 v[100:103], v[164:167], v[196:199], v[100:103]
	v_mfma_f32_16x16x32_bf16 v[96:99], v[180:183], v[196:199], v[96:99]
	v_mfma_f32_16x16x32_bf16 v[84:87], v[164:167], v[204:207], v[84:87]
	v_mfma_f32_16x16x32_bf16 v[80:83], v[180:183], v[204:207], v[80:83]
	v_mfma_f32_16x16x32_bf16 v[68:71], v[164:167], v[212:215], v[68:71]
	v_mfma_f32_16x16x32_bf16 v[64:67], v[180:183], v[212:215], v[64:67]
	s_setprio 0
	s_barrier
; #define PG8_STAGE(bufoff, gbase, voff) do { _Pragma("unroll") for (int _i = 0; _i < 2; ++_i) \
;         __builtin_amdgcn_global_load_lds((const unsigned*)((const char*)(gbase) + (voff)[_i]), (PG8_LAS unsigned*)(lds + (bufoff) + ldsw + _i * 8192), 16, 0, 0); } while (0)
; #define PG8_LDA(dst, b, h) do { _Pragma("unroll") for (int m = 0; m < 4; ++m) _Pragma("unroll") for (int k = 0; k < 2; ++k) dst[m][k] = *(const PG8_LAS bf16x8*)(lds + PG8_SA(b, h) + aoff + m * 2048 + k * 1024); } while (0)
; #define PG8_MMA(ai, bj, At, Bt) do { __builtin_amdgcn_s_setprio(1); _Pragma("unroll") for (int m = 0; m < 4; ++m) _Pragma("unroll") for (int n = 0; n < 2; ++n) _Pragma("unroll") for (int k = 0; k < 2; ++k) \
;         acc[ai][bj][m][n] = __builtin_amdgcn_mfma_f32_16x16x32_bf16(Bt[n][k], At[m][k], acc[ai][bj][m][n], 0, 0, 0); __builtin_amdgcn_s_setprio(0); } while (0)
; #define PG8_WAIT_V(n) asm volatile("s_waitcnt vmcnt(" #n ")" ::: "memory")
; #define PG8_WAIT_L(n) asm volatile("s_waitcnt lgkmcnt(" #n ")" ::: "memory")
; #define PG8_BAR __builtin_amdgcn_s_barrier()
; #define PG8_SCHED __builtin_amdgcn_sched_barrier(0)
; template <class Epi, class Sched, bool ALIGN_EPI = false, bool SP2 = false>
; __device__ __forceinline__ void gemm_phase(PG8_LAS unsigned char* lds, const Gemm g, const Sched& S, const Epi& E, const int wid) {
;     ...
;         for (int t = 0; t < nt; t += 2) {
;             const bool last = (t == nt - 2);
;             const char* a1 = cA + (size_t)(t + 1) * kstep;
;             const char* a2 = last ? nA : cA + (size_t)(t + 2) * kstep; const char* b2 = last ? nB : cB + (size_t)(t + 2) * kstep;
;     ...
;             PG8_LDA(At, 1, 1); PG8_STAGE(PG8_SB(1, 0), b3, voffB); PG8_STAGE(PG8_SB(1, 1), b3 + hstep, voffB); PG8_STAGE(PG8_SA(1, 0), a3, voffA);
;             PG8_WAIT_V(8); PG8_WAIT_L(0); PG8_BAR; PG8_MMA(1, 0, At, B0); PG8_MMA(1, 1, At, B1); PG8_BAR; PG8_SCHED;
	s_add_i32 s26, s54, s33
	v_lshl_add_u64 v[216:217], v[216:217], 0, s[8:9]
	s_mov_b32 m0, s26
	ds_read_b128 v[184:187], v173 offset:49152
	ds_read_b128 v[188:191], v173 offset:50176
	ds_read_b128 v[192:195], v173 offset:51200
	ds_read_b128 v[196:199], v173 offset:52224
	ds_read_b128 v[200:203], v173 offset:53248
	ds_read_b128 v[204:207], v173 offset:54272
	ds_read_b128 v[208:211], v173 offset:55296
	ds_read_b128 v[212:215], v173 offset:56320
	global_load_lds_dwordx4 v[216:217], off
	s_add_i32 m0, s26, 0x2000
	s_add_u32 s24, s24, 0x40080
	v_lshl_add_u64 v[216:217], v[218:219], 0, s[8:9]
	s_addc_u32 s25, s25, 0
	s_add_i32 s26, s55, s33
	global_load_lds_dwordx4 v[216:217], off
	s_mov_b32 m0, s26
	s_nop 0
	global_load_lds_dwordx4 v148, s[24:25]
	s_add_i32 m0, s26, 0x2000
	s_nop 0
	global_load_lds_dwordx4 v144, s[24:25]
	v_lshl_add_u64 v[216:217], v[220:221], 0, s[8:9]
	s_mov_b32 m0, s42
	s_nop 0
	global_load_lds_dwordx4 v[216:217], off
	v_lshl_add_u64 v[216:217], v[222:223], 0, s[8:9]
	s_mov_b32 m0, s43
	s_nop 0
	global_load_lds_dwordx4 v[216:217], off
	s_waitcnt vmcnt(8)
	s_waitcnt lgkmcnt(0)
	s_barrier
	s_setprio 1
	s_waitcnt lgkmcnt(0)
	v_mfma_f32_16x16x32_bf16 v[60:63], v[112:115], v[184:187], v[60:63]
	v_mfma_f32_16x16x32_bf16 v[56:59], v[120:123], v[184:187], v[56:59]
	v_mfma_f32_16x16x32_bf16 v[44:47], v[112:115], v[192:195], v[44:47]
	v_mfma_f32_16x16x32_bf16 v[40:43], v[120:123], v[192:195], v[40:43]
	v_mfma_f32_16x16x32_bf16 v[28:31], v[112:115], v[200:203], v[28:31]
	v_mfma_f32_16x16x32_bf16 v[24:27], v[120:123], v[200:203], v[24:27]
	v_mfma_f32_16x16x32_bf16 v[12:15], v[112:115], v[208:211], v[12:15]
	v_mfma_f32_16x16x32_bf16 v[8:11], v[120:123], v[208:211], v[8:11]
	v_mfma_f32_16x16x32_bf16 v[60:63], v[116:119], v[188:191], v[60:63]
	v_mfma_f32_16x16x32_bf16 v[56:59], v[124:127], v[188:191], v[56:59]
	v_mfma_f32_16x16x32_bf16 v[44:47], v[116:119], v[196:199], v[44:47]
	v_mfma_f32_16x16x32_bf16 v[40:43], v[124:127], v[196:199], v[40:43]
	v_mfma_f32_16x16x32_bf16 v[28:31], v[116:119], v[204:207], v[28:31]
	v_mfma_f32_16x16x32_bf16 v[24:27], v[124:127], v[204:207], v[24:27]
	v_mfma_f32_16x16x32_bf16 v[12:15], v[116:119], v[212:215], v[12:15]
	v_mfma_f32_16x16x32_bf16 v[8:11], v[124:127], v[212:215], v[8:11]
	s_setprio 0
	s_setprio 1
	v_mfma_f32_16x16x32_bf16 v[52:55], v[160:163], v[184:187], v[52:55]
	v_mfma_f32_16x16x32_bf16 v[48:51], v[176:179], v[184:187], v[48:51]
	v_mfma_f32_16x16x32_bf16 v[36:39], v[160:163], v[192:195], v[36:39]
	v_mfma_f32_16x16x32_bf16 v[32:35], v[176:179], v[192:195], v[32:35]
	v_mfma_f32_16x16x32_bf16 v[20:23], v[160:163], v[200:203], v[20:23]
	v_mfma_f32_16x16x32_bf16 v[16:19], v[176:179], v[200:203], v[16:19]
	v_mfma_f32_16x16x32_bf16 v[4:7], v[160:163], v[208:211], v[4:7]
	v_mfma_f32_16x16x32_bf16 v[0:3], v[176:179], v[208:211], v[0:3]
	v_mfma_f32_16x16x32_bf16 v[52:55], v[164:167], v[188:191], v[52:55]
	v_mfma_f32_16x16x32_bf16 v[48:51], v[180:183], v[188:191], v[48:51]
	v_mfma_f32_16x16x32_bf16 v[36:39], v[164:167], v[196:199], v[36:39]
	v_mfma_f32_16x16x32_bf16 v[32:35], v[180:183], v[196:199], v[32:35]
	v_mfma_f32_16x16x32_bf16 v[20:23], v[164:167], v[204:207], v[20:23]
	v_mfma_f32_16x16x32_bf16 v[16:19], v[180:183], v[204:207], v[16:19]
	v_mfma_f32_16x16x32_bf16 v[4:7], v[164:167], v[212:215], v[4:7]
	v_mfma_f32_16x16x32_bf16 v[0:3], v[180:183], v[212:215], v[0:3]
	s_setprio 0
	s_barrier
	s_add_i32 s53, s53, 2
	s_add_u32 s22, s22, 0x100
	s_addc_u32 s23, s23, 0
	s_add_u32 s51, s51, 0x100
	s_addc_u32 s52, s52, 0
	s_cmp_gt_u32 s53, 13
	s_cbranch_scc0 .LBB0_629
	s_and_b64 vcc, exec, s[10:11]
	s_cbranch_vccz .LBB0_632
	s_barrier

; #define PG8_STAGE(bufoff, gbase, voff) do { _Pragma("unroll") for (int _i = 0; _i < 2; ++_i) \
;         __builtin_amdgcn_global_load_lds((const unsigned*)((const char*)(gbase) + (voff)[_i]), (PG8_LAS unsigned*)(lds + (bufoff) + ldsw + _i * 8192), 16, 0, 0); } while (0)
; #define PG8_LDA(dst, b, h) do { _Pragma("unroll") for (int m = 0; m < 4; ++m) _Pragma("unroll") for (int k = 0; k < 2; ++k) dst[m][k] = *(const PG8_LAS bf16x8*)(lds + PG8_SA(b, h) + aoff + m * 2048 + k * 1024); } while (0)
; #define PG8_LDB(dst, b, h) do { _Pragma("unroll") for (int n = 0; n < 2; ++n) _Pragma("unroll") for (int k = 0; k < 2; ++k) dst[n][k] = *(const PG8_LAS bf16x8*)(lds + PG8_SB(b, h) + boff + n * 2048 + k * 1024); } while (0)
; #define PG8_MMA(ai, bj, At, Bt) do { __builtin_amdgcn_s_setprio(1); _Pragma("unroll") for (int m = 0; m < 4; ++m) _Pragma("unroll") for (int n = 0; n < 2; ++n) _Pragma("unroll") for (int k = 0; k < 2; ++k) \
;         acc[ai][bj][m][n] = __builtin_amdgcn_mfma_f32_16x16x32_bf16(Bt[n][k], At[m][k], acc[ai][bj][m][n], 0, 0, 0); __builtin_amdgcn_s_setprio(0); } while (0)
; #define PG8_WAIT_V(n) asm volatile("s_waitcnt vmcnt(" #n ")" ::: "memory")
; #define PG8_WAIT_L(n) asm volatile("s_waitcnt lgkmcnt(" #n ")" ::: "memory")
; #define PG8_BAR __builtin_amdgcn_s_barrier()
; #define PG8_SCHED __builtin_amdgcn_sched_barrier(0)
; template <class Epi, class Sched, bool ALIGN_EPI = false, bool SP2 = false>
; __device__ __forceinline__ void gemm_phase(PG8_LAS unsigned char* lds, const Gemm g, const Sched& S, const Epi& E, const int wid) {
;     ...
;             PG8_LDB(B0, 0, 0); PG8_LDB(B1, 0, 1); PG8_SCHED; PG8_LDA(At, 0, 0); PG8_STAGE(PG8_SA(1, 1), a1 + hstep, voffA);
;             PG8_WAIT_V(8); PG8_WAIT_L(0); PG8_BAR; PG8_MMA(0, 0, At, B0); PG8_MMA(0, 1, At, B1); PG8_BAR; PG8_SCHED;
;             PG8_LDA(At, 0, 1); PG8_STAGE(PG8_SB(0, 0), b2, voffB); PG8_STAGE(PG8_SB(0, 1), b2 + hstep, voffB); PG8_STAGE(PG8_SA(0, 0), a2, voffA);
;             PG8_WAIT_V(8); PG8_WAIT_L(0); PG8_BAR; PG8_MMA(1, 0, At, B0); PG8_MMA(1, 1, At, B1); PG8_BAR; PG8_SCHED;
;             PG8_LDB(B0, 1, 0); PG8_LDB(B1, 1, 1); PG8_SCHED; PG8_LDA(At, 1, 0); PG8_STAGE(PG8_SA(0, 1), a2 + hstep, voffA);
;             PG8_WAIT_V(8); PG8_WAIT_L(0); PG8_BAR; PG8_MMA(0, 0, At, B0); PG8_MMA(0, 1, At, B1); PG8_BAR; PG8_SCHED;
.LBB0_653:
	ds_read_b128 v[128:131], v169
	ds_read_b128 v[150:153], v169 offset:1024
	ds_read_b128 v[154:157], v169 offset:2048
	ds_read_b128 v[158:161], v169 offset:3072
	ds_read_b128 v[162:165], v170
	ds_read_b128 v[174:177], v170 offset:1024
	ds_read_b128 v[178:181], v170 offset:2048
	ds_read_b128 v[182:185], v170 offset:3072
	s_add_u32 s6, s2, 0xfffc0080
	s_addc_u32 s7, s3, -1
	s_cmp_eq_u32 s60, 12
	s_cselect_b32 s9, s11, s7
	s_cselect_b32 s8, s31, s6
	s_cselect_b32 s7, s29, s59
	s_cselect_b32 s6, s40, s41
	s_add_i32 m0, s39, 0xc000
	ds_read_b128 v[186:189], v171
	ds_read_b128 v[190:193], v171 offset:1024
	ds_read_b128 v[194:197], v171 offset:2048
	ds_read_b128 v[198:201], v171 offset:3072
	ds_read_b128 v[202:205], v171 offset:4096
	ds_read_b128 v[206:209], v171 offset:5120
	ds_read_b128 v[210:213], v171 offset:6144
	ds_read_b128 v[214:217], v171 offset:7168
	global_load_lds_dwordx4 v142, s[2:3]
	s_add_i32 m0, s39, 0xe000
	s_nop 0
	global_load_lds_dwordx4 v144, s[2:3]
	s_waitcnt vmcnt(8)
	s_waitcnt lgkmcnt(0)
	s_barrier
	s_setprio 1
	s_waitcnt lgkmcnt(0)
	v_mfma_f32_16x16x32_bf16 v[124:127], v[128:131], v[186:189], v[124:127]
	v_mfma_f32_16x16x32_bf16 v[120:123], v[154:157], v[186:189], v[120:123]
	v_mfma_f32_16x16x32_bf16 v[108:111], v[128:131], v[194:197], v[108:111]
	v_mfma_f32_16x16x32_bf16 v[104:107], v[154:157], v[194:197], v[104:107]
	v_mfma_f32_16x16x32_bf16 v[92:95], v[128:131], v[202:205], v[92:95]
	v_mfma_f32_16x16x32_bf16 v[88:91], v[154:157], v[202:205], v[88:91]
	v_mfma_f32_16x16x32_bf16 v[76:79], v[128:131], v[210:213], v[76:79]
	v_mfma_f32_16x16x32_bf16 v[72:75], v[154:157], v[210:213], v[72:75]
	v_mfma_f32_16x16x32_bf16 v[124:127], v[150:153], v[190:193], v[124:127]
	v_mfma_f32_16x16x32_bf16 v[120:123], v[158:161], v[190:193], v[120:123]
	v_mfma_f32_16x16x32_bf16 v[108:111], v[150:153], v[198:201], v[108:111]
	v_mfma_f32_16x16x32_bf16 v[104:107], v[158:161], v[198:201], v[104:107]
	v_mfma_f32_16x16x32_bf16 v[92:95], v[150:153], v[206:209], v[92:95]
	v_mfma_f32_16x16x32_bf16 v[88:91], v[158:161], v[206:209], v[88:91]
	v_mfma_f32_16x16x32_bf16 v[76:79], v[150:153], v[214:217], v[76:79]
	v_mfma_f32_16x16x32_bf16 v[72:75], v[158:161], v[214:217], v[72:75]
	s_setprio 0
	s_setprio 1
	v_mfma_f32_16x16x32_bf16 v[116:119], v[162:165], v[186:189], v[116:119]
	v_mfma_f32_16x16x32_bf16 v[112:115], v[178:181], v[186:189], v[112:115]
	v_mfma_f32_16x16x32_bf16 v[100:103], v[162:165], v[194:197], v[100:103]
	v_mfma_f32_16x16x32_bf16 v[96:99], v[178:181], v[194:197], v[96:99]
	v_mfma_f32_16x16x32_bf16 v[84:87], v[162:165], v[202:205], v[84:87]
	v_mfma_f32_16x16x32_bf16 v[80:83], v[178:181], v[202:205], v[80:83]
	v_mfma_f32_16x16x32_bf16 v[68:71], v[162:165], v[210:213], v[68:71]
	v_mfma_f32_16x16x32_bf16 v[64:67], v[178:181], v[210:213], v[64:67]
	v_mfma_f32_16x16x32_bf16 v[116:119], v[174:177], v[190:193], v[116:119]
	v_mfma_f32_16x16x32_bf16 v[112:115], v[182:185], v[190:193], v[112:115]
	v_mfma_f32_16x16x32_bf16 v[100:103], v[174:177], v[198:201], v[100:103]
	v_mfma_f32_16x16x32_bf16 v[96:99], v[182:185], v[198:201], v[96:99]
	v_mfma_f32_16x16x32_bf16 v[84:87], v[174:177], v[206:209], v[84:87]
	v_mfma_f32_16x16x32_bf16 v[80:83], v[182:185], v[206:209], v[80:83]
	v_mfma_f32_16x16x32_bf16 v[68:71], v[174:177], v[214:217], v[68:71]
	v_mfma_f32_16x16x32_bf16 v[64:67], v[182:185], v[214:217], v[64:67]
	s_setprio 0
	s_barrier
	s_add_i32 s61, s52, s33
	v_lshl_add_u64 v[132:133], s[6:7], 0, v[136:137]
	s_mov_b32 m0, s61
	ds_read_b128 v[186:189], v171 offset:16384
	ds_read_b128 v[190:193], v171 offset:17408
	ds_read_b128 v[194:197], v171 offset:18432
	ds_read_b128 v[198:201], v171 offset:19456
	ds_read_b128 v[202:205], v171 offset:20480
	ds_read_b128 v[206:209], v171 offset:21504
	ds_read_b128 v[210:213], v171 offset:22528
	ds_read_b128 v[214:217], v171 offset:23552
	global_load_lds_dwordx4 v[132:133], off
	s_add_i32 m0, s61, 0x2000
	s_add_u32 s62, s6, 0x40000
	v_lshl_add_u64 v[218:219], s[6:7], 0, v[140:141]
	s_addc_u32 s63, s7, 0
	s_add_i32 s61, s53, s33
	global_load_lds_dwordx4 v[218:219], off
	s_mov_b32 m0, s61
	v_lshl_add_u64 v[222:223], s[8:9], 0, v[138:139]
	global_load_lds_dwordx4 v136, s[62:63]
	s_add_i32 m0, s61, 0x2000
	s_nop 0
	global_load_lds_dwordx4 v140, s[62:63]
	v_lshl_add_u64 v[220:221], s[8:9], 0, v[134:135]
	s_mov_b32 m0, s39
	s_nop 0
	global_load_lds_dwordx4 v[220:221], off
	s_mov_b32 m0, s45
	s_nop 0
	global_load_lds_dwordx4 v[222:223], off
	s_waitcnt vmcnt(8)
	s_waitcnt lgkmcnt(0)
	s_barrier
	s_setprio 1
	s_waitcnt lgkmcnt(0)
	v_mfma_f32_16x16x32_bf16 v[60:63], v[128:131], v[186:189], v[60:63]
	v_mfma_f32_16x16x32_bf16 v[56:59], v[154:157], v[186:189], v[56:59]
	v_mfma_f32_16x16x32_bf16 v[48:51], v[128:131], v[194:197], v[48:51]
	v_mfma_f32_16x16x32_bf16 v[40:43], v[154:157], v[194:197], v[40:43]
	v_mfma_f32_16x16x32_bf16 v[32:35], v[128:131], v[202:205], v[32:35]
	v_mfma_f32_16x16x32_bf16 v[24:27], v[154:157], v[202:205], v[24:27]
	v_mfma_f32_16x16x32_bf16 v[12:15], v[128:131], v[210:213], v[12:15]
	v_mfma_f32_16x16x32_bf16 v[8:11], v[154:157], v[210:213], v[8:11]
	v_mfma_f32_16x16x32_bf16 v[60:63], v[150:153], v[190:193], v[60:63]
	v_mfma_f32_16x16x32_bf16 v[56:59], v[158:161], v[190:193], v[56:59]
	v_mfma_f32_16x16x32_bf16 v[48:51], v[150:153], v[198:201], v[48:51]
	v_mfma_f32_16x16x32_bf16 v[40:43], v[158:161], v[198:201], v[40:43]
	v_mfma_f32_16x16x32_bf16 v[32:35], v[150:153], v[206:209], v[32:35]
	v_mfma_f32_16x16x32_bf16 v[24:27], v[158:161], v[206:209], v[24:27]
	v_mfma_f32_16x16x32_bf16 v[12:15], v[150:153], v[214:217], v[12:15]
	v_mfma_f32_16x16x32_bf16 v[8:11], v[158:161], v[214:217], v[8:11]
	s_setprio 0
	s_setprio 1
	v_mfma_f32_16x16x32_bf16 v[52:55], v[162:165], v[186:189], v[52:55]
	v_mfma_f32_16x16x32_bf16 v[44:47], v[178:181], v[186:189], v[44:47]
	v_mfma_f32_16x16x32_bf16 v[36:39], v[162:165], v[194:197], v[36:39]
	v_mfma_f32_16x16x32_bf16 v[28:31], v[178:181], v[194:197], v[28:31]
	v_mfma_f32_16x16x32_bf16 v[20:23], v[162:165], v[202:205], v[20:23]
	v_mfma_f32_16x16x32_bf16 v[16:19], v[178:181], v[202:205], v[16:19]
	v_mfma_f32_16x16x32_bf16 v[4:7], v[162:165], v[210:213], v[4:7]
	v_mfma_f32_16x16x32_bf16 v[0:3], v[178:181], v[210:213], v[0:3]
	v_mfma_f32_16x16x32_bf16 v[52:55], v[174:177], v[190:193], v[52:55]
	v_mfma_f32_16x16x32_bf16 v[44:47], v[182:185], v[190:193], v[44:47]
	v_mfma_f32_16x16x32_bf16 v[36:39], v[174:177], v[198:201], v[36:39]
	v_mfma_f32_16x16x32_bf16 v[28:31], v[182:185], v[198:201], v[28:31]
	v_mfma_f32_16x16x32_bf16 v[20:23], v[174:177], v[206:209], v[20:23]
	v_mfma_f32_16x16x32_bf16 v[16:19], v[182:185], v[206:209], v[16:19]
	v_mfma_f32_16x16x32_bf16 v[4:7], v[174:177], v[214:217], v[4:7]
	v_mfma_f32_16x16x32_bf16 v[0:3], v[182:185], v[214:217], v[0:3]
	s_setprio 0
	s_barrier
; #define PG8_STAGE(bufoff, gbase, voff) do { _Pragma("unroll") for (int _i = 0; _i < 2; ++_i) \
;         __builtin_amdgcn_global_load_lds((const unsigned*)((const char*)(gbase) + (voff)[_i]), (PG8_LAS unsigned*)(lds + (bufoff) + ldsw + _i * 8192), 16, 0, 0); } while (0)
; #define PG8_LDA(dst, b, h) do { _Pragma("unroll") for (int m = 0; m < 4; ++m) _Pragma("unroll") for (int k = 0; k < 2; ++k) dst[m][k] = *(const PG8_LAS bf16x8*)(lds + PG8_SA(b, h) + aoff + m * 2048 + k * 1024); } while (0)
; #define PG8_LDB(dst, b, h) do { _Pragma("unroll") for (int n = 0; n < 2; ++n) _Pragma("unroll") for (int k = 0; k < 2; ++k) dst[n][k] = *(const PG8_LAS bf16x8*)(lds + PG8_SB(b, h) + boff + n * 2048 + k * 1024); } while (0)
; #define PG8_MMA(ai, bj, At, Bt) do { __builtin_amdgcn_s_setprio(1); _Pragma("unroll") for (int m = 0; m < 4; ++m) _Pragma("unroll") for (int n = 0; n < 2; ++n) _Pragma("unroll") for (int k = 0; k < 2; ++k) \
;         acc[ai][bj][m][n] = __builtin_amdgcn_mfma_f32_16x16x32_bf16(Bt[n][k], At[m][k], acc[ai][bj][m][n], 0, 0, 0); __builtin_amdgcn_s_setprio(0); } while (0)
; #define PG8_WAIT_V(n) asm volatile("s_waitcnt vmcnt(" #n ")" ::: "memory")
; #define PG8_WAIT_L(n) asm volatile("s_waitcnt lgkmcnt(" #n ")" ::: "memory")
; #define PG8_BAR __builtin_amdgcn_s_barrier()
; #define PG8_SCHED __builtin_amdgcn_sched_barrier(0)
; template <class Epi, class Sched, bool ALIGN_EPI = false, bool SP2 = false>
; __device__ __forceinline__ void gemm_phase(PG8_LAS unsigned char* lds, const Gemm g, const Sched& S, const Epi& E, const int wid) {
;     ...
;         for (int t = 0; t < nt; t += 2) {
;             const bool last = (t == nt - 2);
;             const char* a1 = cA + (size_t)(t + 1) * kstep;
;             const char* a2 = last ? nA : cA + (size_t)(t + 2) * kstep; const char* b2 = last ? nB : cB + (size_t)(t + 2) * kstep;
;     ...
;             PG8_LDB(B0, 1, 0); PG8_LDB(B1, 1, 1); PG8_SCHED; PG8_LDA(At, 1, 0); PG8_STAGE(PG8_SA(0, 1), a2 + hstep, voffA);
;             PG8_WAIT_V(8); PG8_WAIT_L(0); PG8_BAR; PG8_MMA(0, 0, At, B0); PG8_MMA(0, 1, At, B1); PG8_BAR; PG8_SCHED;
;             PG8_LDA(At, 1, 1); PG8_STAGE(PG8_SB(1, 0), b3, voffB); PG8_STAGE(PG8_SB(1, 1), b3 + hstep, voffB); PG8_STAGE(PG8_SA(1, 0), a3, voffA);
;             PG8_WAIT_V(8); PG8_WAIT_L(0); PG8_BAR; PG8_MMA(1, 0, At, B0); PG8_MMA(1, 1, At, B1); PG8_BAR; PG8_SCHED;
	s_add_i32 s61, 0, 0x18000
	s_add_i32 s62, 0, 0x1c000
	v_add_u32_e32 v158, s61, v167
	v_add_u32_e32 v182, s62, v167
	ds_read_b128 v[128:131], v158
	ds_read_b128 v[150:153], v158 offset:1024
	ds_read_b128 v[154:157], v158 offset:2048
	ds_read_b128 v[158:161], v158 offset:3072
	ds_read_b128 v[162:165], v182
	ds_read_b128 v[174:177], v182 offset:1024
	ds_read_b128 v[178:181], v182 offset:2048
	ds_read_b128 v[182:185], v182 offset:3072
	s_add_u32 s8, s8, 0x40000
	s_addc_u32 s9, s9, 0
	s_mov_b32 m0, s46
	ds_read_b128 v[186:189], v171 offset:32768
	ds_read_b128 v[190:193], v171 offset:33792
	ds_read_b128 v[194:197], v171 offset:34816
	ds_read_b128 v[198:201], v171 offset:35840
	ds_read_b128 v[202:205], v171 offset:36864
	ds_read_b128 v[206:209], v171 offset:37888
	ds_read_b128 v[210:213], v171 offset:38912
	ds_read_b128 v[214:217], v171 offset:39936
	global_load_lds_dwordx4 v134, s[8:9]
	s_mov_b32 m0, s47
	s_nop 0
	global_load_lds_dwordx4 v138, s[8:9]
	s_waitcnt vmcnt(8)
	s_waitcnt lgkmcnt(0)
	s_barrier
	s_setprio 1
	s_waitcnt lgkmcnt(0)
	v_mfma_f32_16x16x32_bf16 v[124:127], v[128:131], v[186:189], v[124:127]
	v_mfma_f32_16x16x32_bf16 v[120:123], v[154:157], v[186:189], v[120:123]
	v_mfma_f32_16x16x32_bf16 v[108:111], v[128:131], v[194:197], v[108:111]
	v_mfma_f32_16x16x32_bf16 v[104:107], v[154:157], v[194:197], v[104:107]
	v_mfma_f32_16x16x32_bf16 v[92:95], v[128:131], v[202:205], v[92:95]
	v_mfma_f32_16x16x32_bf16 v[88:91], v[154:157], v[202:205], v[88:91]
	v_mfma_f32_16x16x32_bf16 v[76:79], v[128:131], v[210:213], v[76:79]
	v_mfma_f32_16x16x32_bf16 v[72:75], v[154:157], v[210:213], v[72:75]
	v_mfma_f32_16x16x32_bf16 v[124:127], v[150:153], v[190:193], v[124:127]
	v_mfma_f32_16x16x32_bf16 v[120:123], v[158:161], v[190:193], v[120:123]
	v_mfma_f32_16x16x32_bf16 v[108:111], v[150:153], v[198:201], v[108:111]
	v_mfma_f32_16x16x32_bf16 v[104:107], v[158:161], v[198:201], v[104:107]
	v_mfma_f32_16x16x32_bf16 v[92:95], v[150:153], v[206:209], v[92:95]
	v_mfma_f32_16x16x32_bf16 v[88:91], v[158:161], v[206:209], v[88:91]
	v_mfma_f32_16x16x32_bf16 v[76:79], v[150:153], v[214:217], v[76:79]
	v_mfma_f32_16x16x32_bf16 v[72:75], v[158:161], v[214:217], v[72:75]
	s_setprio 0
	s_setprio 1
	v_mfma_f32_16x16x32_bf16 v[116:119], v[162:165], v[186:189], v[116:119]
	v_mfma_f32_16x16x32_bf16 v[112:115], v[178:181], v[186:189], v[112:115]
	v_mfma_f32_16x16x32_bf16 v[100:103], v[162:165], v[194:197], v[100:103]
	v_mfma_f32_16x16x32_bf16 v[96:99], v[178:181], v[194:197], v[96:99]
	v_mfma_f32_16x16x32_bf16 v[84:87], v[162:165], v[202:205], v[84:87]
	v_mfma_f32_16x16x32_bf16 v[80:83], v[178:181], v[202:205], v[80:83]
	v_mfma_f32_16x16x32_bf16 v[68:71], v[162:165], v[210:213], v[68:71]
	v_mfma_f32_16x16x32_bf16 v[64:67], v[178:181], v[210:213], v[64:67]
	v_mfma_f32_16x16x32_bf16 v[116:119], v[174:177], v[190:193], v[116:119]
	v_mfma_f32_16x16x32_bf16 v[112:115], v[182:185], v[190:193], v[112:115]
	v_mfma_f32_16x16x32_bf16 v[100:103], v[174:177], v[198:201], v[100:103]
	v_mfma_f32_16x16x32_bf16 v[96:99], v[182:185], v[198:201], v[96:99]
	v_mfma_f32_16x16x32_bf16 v[84:87], v[174:177], v[206:209], v[84:87]
	v_mfma_f32_16x16x32_bf16 v[80:83], v[182:185], v[206:209], v[80:83]
	v_mfma_f32_16x16x32_bf16 v[68:71], v[174:177], v[214:217], v[68:71]
	v_mfma_f32_16x16x32_bf16 v[64:67], v[182:185], v[214:217], v[64:67]
	s_setprio 0
	s_barrier
	s_add_i32 s8, s61, s33
	v_lshl_add_u64 v[132:133], v[132:133], 0, s[16:17]
	s_mov_b32 m0, s8
	ds_read_b128 v[186:189], v171 offset:49152
	ds_read_b128 v[190:193], v171 offset:50176
	ds_read_b128 v[194:197], v171 offset:51200
	ds_read_b128 v[198:201], v171 offset:52224
	ds_read_b128 v[202:205], v171 offset:53248
	ds_read_b128 v[206:209], v171 offset:54272
	ds_read_b128 v[210:213], v171 offset:55296
	ds_read_b128 v[214:217], v171 offset:56320
	global_load_lds_dwordx4 v[132:133], off
	s_add_i32 m0, s8, 0x2000
	s_add_u32 s6, s6, 0x40080
	v_lshl_add_u64 v[132:133], v[218:219], 0, s[16:17]
	s_addc_u32 s7, s7, 0
	s_add_i32 s8, s62, s33
	global_load_lds_dwordx4 v[132:133], off
	s_mov_b32 m0, s8
	s_nop 0
	global_load_lds_dwordx4 v136, s[6:7]
	s_add_i32 m0, s8, 0x2000
	s_nop 0
	global_load_lds_dwordx4 v140, s[6:7]
	v_lshl_add_u64 v[132:133], v[220:221], 0, s[16:17]
	s_mov_b32 m0, s49
	s_nop 0
	global_load_lds_dwordx4 v[132:133], off
	v_lshl_add_u64 v[132:133], v[222:223], 0, s[16:17]
	s_mov_b32 m0, s50
	s_nop 0
	global_load_lds_dwordx4 v[132:133], off
	s_waitcnt vmcnt(8)
	s_waitcnt lgkmcnt(0)
	s_barrier
	s_setprio 1
	s_waitcnt lgkmcnt(0)
	v_mfma_f32_16x16x32_bf16 v[60:63], v[128:131], v[186:189], v[60:63]
	v_mfma_f32_16x16x32_bf16 v[56:59], v[154:157], v[186:189], v[56:59]
	v_mfma_f32_16x16x32_bf16 v[48:51], v[128:131], v[194:197], v[48:51]
	v_mfma_f32_16x16x32_bf16 v[40:43], v[154:157], v[194:197], v[40:43]
	v_mfma_f32_16x16x32_bf16 v[32:35], v[128:131], v[202:205], v[32:35]
	v_mfma_f32_16x16x32_bf16 v[24:27], v[154:157], v[202:205], v[24:27]
	v_mfma_f32_16x16x32_bf16 v[12:15], v[128:131], v[210:213], v[12:15]
	v_mfma_f32_16x16x32_bf16 v[8:11], v[154:157], v[210:213], v[8:11]
	v_mfma_f32_16x16x32_bf16 v[60:63], v[150:153], v[190:193], v[60:63]
	v_mfma_f32_16x16x32_bf16 v[56:59], v[158:161], v[190:193], v[56:59]
	v_mfma_f32_16x16x32_bf16 v[48:51], v[150:153], v[198:201], v[48:51]
	v_mfma_f32_16x16x32_bf16 v[40:43], v[158:161], v[198:201], v[40:43]
	v_mfma_f32_16x16x32_bf16 v[32:35], v[150:153], v[206:209], v[32:35]
	v_mfma_f32_16x16x32_bf16 v[24:27], v[158:161], v[206:209], v[24:27]
	v_mfma_f32_16x16x32_bf16 v[12:15], v[150:153], v[214:217], v[12:15]
	v_mfma_f32_16x16x32_bf16 v[8:11], v[158:161], v[214:217], v[8:11]
	s_setprio 0
	s_setprio 1
	v_mfma_f32_16x16x32_bf16 v[52:55], v[162:165], v[186:189], v[52:55]
	v_mfma_f32_16x16x32_bf16 v[44:47], v[178:181], v[186:189], v[44:47]
	v_mfma_f32_16x16x32_bf16 v[36:39], v[162:165], v[194:197], v[36:39]
	v_mfma_f32_16x16x32_bf16 v[28:31], v[178:181], v[194:197], v[28:31]
	v_mfma_f32_16x16x32_bf16 v[20:23], v[162:165], v[202:205], v[20:23]
	v_mfma_f32_16x16x32_bf16 v[16:19], v[178:181], v[202:205], v[16:19]
	v_mfma_f32_16x16x32_bf16 v[4:7], v[162:165], v[210:213], v[4:7]
	v_mfma_f32_16x16x32_bf16 v[0:3], v[178:181], v[210:213], v[0:3]
	v_mfma_f32_16x16x32_bf16 v[52:55], v[174:177], v[190:193], v[52:55]
	v_mfma_f32_16x16x32_bf16 v[44:47], v[182:185], v[190:193], v[44:47]
	v_mfma_f32_16x16x32_bf16 v[36:39], v[174:177], v[198:201], v[36:39]
	v_mfma_f32_16x16x32_bf16 v[28:31], v[182:185], v[198:201], v[28:31]
	v_mfma_f32_16x16x32_bf16 v[20:23], v[174:177], v[206:209], v[20:23]
	v_mfma_f32_16x16x32_bf16 v[16:19], v[182:185], v[206:209], v[16:19]
	v_mfma_f32_16x16x32_bf16 v[4:7], v[174:177], v[214:217], v[4:7]
	v_mfma_f32_16x16x32_bf16 v[0:3], v[182:185], v[214:217], v[0:3]
	s_setprio 0
	s_barrier
	s_add_i32 s60, s60, 2
	s_add_u32 s2, s2, 0x100
	s_addc_u32 s3, s3, 0
	s_add_u32 s41, s41, 0x100
	s_addc_u32 s59, s59, 0
	s_cmp_gt_u32 s60, 13
	s_cbranch_scc0 .LBB0_653
	s_and_b64 vcc, exec, s[18:19]
	s_cbranch_vccz .LBB0_656
	s_barrier

; #define PG8_STAGE(bufoff, gbase, voff) do { _Pragma("unroll") for (int _i = 0; _i < 2; ++_i) \
;         __builtin_amdgcn_global_load_lds((const unsigned*)((const char*)(gbase) + (voff)[_i]), (PG8_LAS unsigned*)(lds + (bufoff) + ldsw + _i * 8192), 16, 0, 0); } while (0)
; #define PG8_LDA(dst, b, h) do { _Pragma("unroll") for (int m = 0; m < 4; ++m) _Pragma("unroll") for (int k = 0; k < 2; ++k) dst[m][k] = *(const PG8_LAS bf16x8*)(lds + PG8_SA(b, h) + aoff + m * 2048 + k * 1024); } while (0)
; #define PG8_LDB(dst, b, h) do { _Pragma("unroll") for (int n = 0; n < 2; ++n) _Pragma("unroll") for (int k = 0; k < 2; ++k) dst[n][k] = *(const PG8_LAS bf16x8*)(lds + PG8_SB(b, h) + boff + n * 2048 + k * 1024); } while (0)
; #define PG8_MMA(ai, bj, At, Bt) do { __builtin_amdgcn_s_setprio(1); _Pragma("unroll") for (int m = 0; m < 4; ++m) _Pragma("unroll") for (int n = 0; n < 2; ++n) _Pragma("unroll") for (int k = 0; k < 2; ++k) \
;         acc[ai][bj][m][n] = __builtin_amdgcn_mfma_f32_16x16x32_bf16(Bt[n][k], At[m][k], acc[ai][bj][m][n], 0, 0, 0); __builtin_amdgcn_s_setprio(0); } while (0)
; #define PG8_WAIT_V(n) asm volatile("s_waitcnt vmcnt(" #n ")" ::: "memory")
; #define PG8_WAIT_L(n) asm volatile("s_waitcnt lgkmcnt(" #n ")" ::: "memory")
; #define PG8_BAR __builtin_amdgcn_s_barrier()
; #define PG8_SCHED __builtin_amdgcn_sched_barrier(0)
; template <class Epi, class Sched, bool ALIGN_EPI = false, bool SP2 = false>
; __device__ __forceinline__ void gemm_phase(PG8_LAS unsigned char* lds, const Gemm g, const Sched& S, const Epi& E, const int wid) {
;     ...
;             PG8_LDB(B0, 0, 0); PG8_LDB(B1, 0, 1); PG8_SCHED; PG8_LDA(At, 0, 0); PG8_STAGE(PG8_SA(1, 1), a1 + hstep, voffA);
;             PG8_WAIT_V(8); PG8_WAIT_L(0); PG8_BAR; PG8_MMA(0, 0, At, B0); PG8_MMA(0, 1, At, B1); PG8_BAR; PG8_SCHED;
;             PG8_LDA(At, 0, 1); PG8_STAGE(PG8_SB(0, 0), b2, voffB); PG8_STAGE(PG8_SB(0, 1), b2 + hstep, voffB); PG8_STAGE(PG8_SA(0, 0), a2, voffA);
;             PG8_WAIT_V(8); PG8_WAIT_L(0); PG8_BAR; PG8_MMA(1, 0, At, B0); PG8_MMA(1, 1, At, B1); PG8_BAR; PG8_SCHED;
.LBB0_816:
	ds_read_b128 v[104:107], v161
	ds_read_b128 v[108:111], v161 offset:1024
	ds_read_b128 v[148:151], v161 offset:2048
	ds_read_b128 v[152:155], v161 offset:3072
	ds_read_b128 v[166:169], v162
	ds_read_b128 v[170:173], v162 offset:1024
	ds_read_b128 v[174:177], v162 offset:2048
	ds_read_b128 v[178:181], v162 offset:3072
	s_add_u32 s40, s38, 0xfffc0080
	s_addc_u32 s41, s39, -1
	s_cmp_eq_u32 s69, 12
	s_cselect_b32 s43, s29, s41
	s_cselect_b32 s42, s65, s40
	s_cselect_b32 s41, s27, s68
	s_cselect_b32 s40, s66, s67
	s_add_i32 m0, s37, 0xc000
	ds_read_b128 v[182:185], v163
	ds_read_b128 v[186:189], v163 offset:1024
	ds_read_b128 v[190:193], v163 offset:2048
	ds_read_b128 v[194:197], v163 offset:3072
	ds_read_b128 v[198:201], v163 offset:4096
	ds_read_b128 v[202:205], v163 offset:5120
	ds_read_b128 v[206:209], v163 offset:6144
	ds_read_b128 v[210:213], v163 offset:7168
	global_load_lds_dwordx4 v140, s[38:39]
	s_add_i32 m0, s37, 0xe000
	s_nop 0
	global_load_lds_dwordx4 v142, s[38:39]
	s_waitcnt vmcnt(8)
	s_waitcnt lgkmcnt(0)
	s_barrier
	s_setprio 1
	s_waitcnt lgkmcnt(0)
	v_mfma_f32_16x16x32_bf16 v[132:135], v[104:107], v[182:185], v[132:135]
	v_mfma_f32_16x16x32_bf16 v[128:131], v[148:151], v[182:185], v[128:131]
	v_mfma_f32_16x16x32_bf16 v[116:119], v[104:107], v[190:193], v[116:119]
	v_mfma_f32_16x16x32_bf16 v[112:115], v[148:151], v[190:193], v[112:115]
	v_mfma_f32_16x16x32_bf16 v[92:95], v[104:107], v[198:201], v[92:95]
	v_mfma_f32_16x16x32_bf16 v[88:91], v[148:151], v[198:201], v[88:91]
	v_mfma_f32_16x16x32_bf16 v[76:79], v[104:107], v[206:209], v[76:79]
	v_mfma_f32_16x16x32_bf16 v[72:75], v[148:151], v[206:209], v[72:75]
	v_mfma_f32_16x16x32_bf16 v[132:135], v[108:111], v[186:189], v[132:135]
	v_mfma_f32_16x16x32_bf16 v[128:131], v[152:155], v[186:189], v[128:131]
	v_mfma_f32_16x16x32_bf16 v[116:119], v[108:111], v[194:197], v[116:119]
	v_mfma_f32_16x16x32_bf16 v[112:115], v[152:155], v[194:197], v[112:115]
	v_mfma_f32_16x16x32_bf16 v[92:95], v[108:111], v[202:205], v[92:95]
	v_mfma_f32_16x16x32_bf16 v[88:91], v[152:155], v[202:205], v[88:91]
	v_mfma_f32_16x16x32_bf16 v[76:79], v[108:111], v[210:213], v[76:79]
	v_mfma_f32_16x16x32_bf16 v[72:75], v[152:155], v[210:213], v[72:75]
	s_setprio 0
	s_setprio 1
	v_mfma_f32_16x16x32_bf16 v[124:127], v[166:169], v[182:185], v[124:127]
	v_mfma_f32_16x16x32_bf16 v[120:123], v[174:177], v[182:185], v[120:123]
	v_mfma_f32_16x16x32_bf16 v[100:103], v[166:169], v[190:193], v[100:103]
	v_mfma_f32_16x16x32_bf16 v[96:99], v[174:177], v[190:193], v[96:99]
	v_mfma_f32_16x16x32_bf16 v[84:87], v[166:169], v[198:201], v[84:87]
	v_mfma_f32_16x16x32_bf16 v[80:83], v[174:177], v[198:201], v[80:83]
	v_mfma_f32_16x16x32_bf16 v[68:71], v[166:169], v[206:209], v[68:71]
	v_mfma_f32_16x16x32_bf16 v[64:67], v[174:177], v[206:209], v[64:67]
	v_mfma_f32_16x16x32_bf16 v[124:127], v[170:173], v[186:189], v[124:127]
	v_mfma_f32_16x16x32_bf16 v[120:123], v[178:181], v[186:189], v[120:123]
	v_mfma_f32_16x16x32_bf16 v[100:103], v[170:173], v[194:197], v[100:103]
	v_mfma_f32_16x16x32_bf16 v[96:99], v[178:181], v[194:197], v[96:99]
	v_mfma_f32_16x16x32_bf16 v[84:87], v[170:173], v[202:205], v[84:87]
	v_mfma_f32_16x16x32_bf16 v[80:83], v[178:181], v[202:205], v[80:83]
	v_mfma_f32_16x16x32_bf16 v[68:71], v[170:173], v[210:213], v[68:71]
	v_mfma_f32_16x16x32_bf16 v[64:67], v[178:181], v[210:213], v[64:67]
	s_setprio 0
	s_barrier
	s_add_i32 s70, s54, s44
	v_lshl_add_u64 v[156:157], s[40:41], 0, v[136:137]
	s_mov_b32 m0, s70
	ds_read_b128 v[182:185], v163 offset:16384
	ds_read_b128 v[186:189], v163 offset:17408
	ds_read_b128 v[190:193], v163 offset:18432
	ds_read_b128 v[194:197], v163 offset:19456
	ds_read_b128 v[198:201], v163 offset:20480
	ds_read_b128 v[202:205], v163 offset:21504
	ds_read_b128 v[206:209], v163 offset:22528
	ds_read_b128 v[210:213], v163 offset:23552
	global_load_lds_dwordx4 v[156:157], off
	s_add_i32 m0, s70, 0x2000
	s_add_u32 s70, s40, 0x40000
	v_lshl_add_u64 v[214:215], s[40:41], 0, v[138:139]
	s_addc_u32 s71, s41, 0
	s_add_i32 s72, s55, s44
	global_load_lds_dwordx4 v[214:215], off
	s_mov_b32 m0, s72
	v_lshl_add_u64 v[218:219], s[42:43], 0, v[138:139]
	global_load_lds_dwordx4 v136, s[70:71]
	s_add_i32 m0, s72, 0x2000
	s_nop 0
	global_load_lds_dwordx4 v138, s[70:71]
	v_lshl_add_u64 v[216:217], s[42:43], 0, v[136:137]
	s_mov_b32 m0, s37
	s_nop 0
	global_load_lds_dwordx4 v[216:217], off
	s_mov_b32 m0, s45
	s_nop 0
	global_load_lds_dwordx4 v[218:219], off
	s_waitcnt vmcnt(8)
	s_waitcnt lgkmcnt(0)
	s_barrier
; #define PG8_STAGE(bufoff, gbase, voff) do { _Pragma("unroll") for (int _i = 0; _i < 2; ++_i) \
;         __builtin_amdgcn_global_load_lds((const unsigned*)((const char*)(gbase) + (voff)[_i]), (PG8_LAS unsigned*)(lds + (bufoff) + ldsw + _i * 8192), 16, 0, 0); } while (0)
; #define PG8_LDA(dst, b, h) do { _Pragma("unroll") for (int m = 0; m < 4; ++m) _Pragma("unroll") for (int k = 0; k < 2; ++k) dst[m][k] = *(const PG8_LAS bf16x8*)(lds + PG8_SA(b, h) + aoff + m * 2048 + k * 1024); } while (0)
; #define PG8_LDB(dst, b, h) do { _Pragma("unroll") for (int n = 0; n < 2; ++n) _Pragma("unroll") for (int k = 0; k < 2; ++k) dst[n][k] = *(const PG8_LAS bf16x8*)(lds + PG8_SB(b, h) + boff + n * 2048 + k * 1024); } while (0)
; #define PG8_MMA(ai, bj, At, Bt) do { __builtin_amdgcn_s_setprio(1); _Pragma("unroll") for (int m = 0; m < 4; ++m) _Pragma("unroll") for (int n = 0; n < 2; ++n) _Pragma("unroll") for (int k = 0; k < 2; ++k) \
;         acc[ai][bj][m][n] = __builtin_amdgcn_mfma_f32_16x16x32_bf16(Bt[n][k], At[m][k], acc[ai][bj][m][n], 0, 0, 0); __builtin_amdgcn_s_setprio(0); } while (0)
; #define PG8_WAIT_V(n) asm volatile("s_waitcnt vmcnt(" #n ")" ::: "memory")
; #define PG8_WAIT_L(n) asm volatile("s_waitcnt lgkmcnt(" #n ")" ::: "memory")
; #define PG8_BAR __builtin_amdgcn_s_barrier()
; #define PG8_SCHED __builtin_amdgcn_sched_barrier(0)
; template <class Epi, class Sched, bool ALIGN_EPI = false, bool SP2 = false>
; __device__ __forceinline__ void gemm_phase(PG8_LAS unsigned char* lds, const Gemm g, const Sched& S, const Epi& E, const int wid) {
;     ...
;             PG8_LDA(At, 0, 1); PG8_STAGE(PG8_SB(0, 0), b2, voffB); PG8_STAGE(PG8_SB(0, 1), b2 + hstep, voffB); PG8_STAGE(PG8_SA(0, 0), a2, voffA);
;             PG8_WAIT_V(8); PG8_WAIT_L(0); PG8_BAR; PG8_MMA(1, 0, At, B0); PG8_MMA(1, 1, At, B1); PG8_BAR; PG8_SCHED;
;             PG8_LDB(B0, 1, 0); PG8_LDB(B1, 1, 1); PG8_SCHED; PG8_LDA(At, 1, 0); PG8_STAGE(PG8_SA(0, 1), a2 + hstep, voffA);
;             PG8_WAIT_V(8); PG8_WAIT_L(0); PG8_BAR; PG8_MMA(0, 0, At, B0); PG8_MMA(0, 1, At, B1); PG8_BAR; PG8_SCHED;
	s_setprio 1
	s_waitcnt lgkmcnt(0)
	v_mfma_f32_16x16x32_bf16 v[60:63], v[104:107], v[182:185], v[60:63]
	v_mfma_f32_16x16x32_bf16 v[56:59], v[148:151], v[182:185], v[56:59]
	v_mfma_f32_16x16x32_bf16 v[44:47], v[104:107], v[190:193], v[44:47]
	v_mfma_f32_16x16x32_bf16 v[40:43], v[148:151], v[190:193], v[40:43]
	v_mfma_f32_16x16x32_bf16 v[28:31], v[104:107], v[198:201], v[28:31]
	v_mfma_f32_16x16x32_bf16 v[24:27], v[148:151], v[198:201], v[24:27]
	v_mfma_f32_16x16x32_bf16 v[20:23], v[104:107], v[206:209], v[20:23]
	v_mfma_f32_16x16x32_bf16 v[12:15], v[148:151], v[206:209], v[12:15]
	v_mfma_f32_16x16x32_bf16 v[60:63], v[108:111], v[186:189], v[60:63]
	v_mfma_f32_16x16x32_bf16 v[56:59], v[152:155], v[186:189], v[56:59]
	v_mfma_f32_16x16x32_bf16 v[44:47], v[108:111], v[194:197], v[44:47]
	v_mfma_f32_16x16x32_bf16 v[40:43], v[152:155], v[194:197], v[40:43]
	v_mfma_f32_16x16x32_bf16 v[28:31], v[108:111], v[202:205], v[28:31]
	v_mfma_f32_16x16x32_bf16 v[24:27], v[152:155], v[202:205], v[24:27]
	v_mfma_f32_16x16x32_bf16 v[20:23], v[108:111], v[210:213], v[20:23]
	v_mfma_f32_16x16x32_bf16 v[12:15], v[152:155], v[210:213], v[12:15]
	s_setprio 0
	s_setprio 1
	v_mfma_f32_16x16x32_bf16 v[52:55], v[166:169], v[182:185], v[52:55]
	v_mfma_f32_16x16x32_bf16 v[48:51], v[174:177], v[182:185], v[48:51]
	v_mfma_f32_16x16x32_bf16 v[36:39], v[166:169], v[190:193], v[36:39]
	v_mfma_f32_16x16x32_bf16 v[32:35], v[174:177], v[190:193], v[32:35]
	v_mfma_f32_16x16x32_bf16 v[16:19], v[166:169], v[198:201], v[16:19]
	v_mfma_f32_16x16x32_bf16 v[8:11], v[174:177], v[198:201], v[8:11]
	v_mfma_f32_16x16x32_bf16 v[4:7], v[166:169], v[206:209], v[4:7]
	v_mfma_f32_16x16x32_bf16 v[0:3], v[174:177], v[206:209], v[0:3]
	v_mfma_f32_16x16x32_bf16 v[52:55], v[170:173], v[186:189], v[52:55]
	v_mfma_f32_16x16x32_bf16 v[48:51], v[178:181], v[186:189], v[48:51]
	v_mfma_f32_16x16x32_bf16 v[36:39], v[170:173], v[194:197], v[36:39]
	v_mfma_f32_16x16x32_bf16 v[32:35], v[178:181], v[194:197], v[32:35]
	v_mfma_f32_16x16x32_bf16 v[16:19], v[170:173], v[202:205], v[16:19]
	v_mfma_f32_16x16x32_bf16 v[8:11], v[178:181], v[202:205], v[8:11]
	v_mfma_f32_16x16x32_bf16 v[4:7], v[170:173], v[210:213], v[4:7]
	v_mfma_f32_16x16x32_bf16 v[0:3], v[178:181], v[210:213], v[0:3]
	s_setprio 0
	s_barrier
	s_add_i32 s70, 0, 0x18000
	s_add_i32 s71, 0, 0x1c000
	v_add_u32_e32 v152, s70, v158
	v_add_u32_e32 v165, s71, v158
	ds_read_b128 v[104:107], v152
	ds_read_b128 v[108:111], v152 offset:1024
	ds_read_b128 v[148:151], v152 offset:2048
	ds_read_b128 v[152:155], v152 offset:3072
	ds_read_b128 v[166:169], v165
	ds_read_b128 v[170:173], v165 offset:1024
	ds_read_b128 v[174:177], v165 offset:2048
	ds_read_b128 v[178:181], v165 offset:3072
	s_add_u32 s42, s42, 0x40000
	s_addc_u32 s43, s43, 0
	s_mov_b32 m0, s46
	ds_read_b128 v[182:185], v163 offset:32768
	ds_read_b128 v[186:189], v163 offset:33792
	ds_read_b128 v[190:193], v163 offset:34816
	ds_read_b128 v[194:197], v163 offset:35840
	ds_read_b128 v[198:201], v163 offset:36864
	ds_read_b128 v[202:205], v163 offset:37888
	ds_read_b128 v[206:209], v163 offset:38912
	ds_read_b128 v[210:213], v163 offset:39936
	global_load_lds_dwordx4 v136, s[42:43]
	s_mov_b32 m0, s47
	s_nop 0
	global_load_lds_dwordx4 v138, s[42:43]
	s_waitcnt vmcnt(8)
	s_waitcnt lgkmcnt(0)
	s_barrier
	s_setprio 1
	s_waitcnt lgkmcnt(0)
	v_mfma_f32_16x16x32_bf16 v[132:135], v[104:107], v[182:185], v[132:135]
	v_mfma_f32_16x16x32_bf16 v[128:131], v[148:151], v[182:185], v[128:131]
	v_mfma_f32_16x16x32_bf16 v[116:119], v[104:107], v[190:193], v[116:119]
	v_mfma_f32_16x16x32_bf16 v[112:115], v[148:151], v[190:193], v[112:115]
	v_mfma_f32_16x16x32_bf16 v[92:95], v[104:107], v[198:201], v[92:95]
	v_mfma_f32_16x16x32_bf16 v[88:91], v[148:151], v[198:201], v[88:91]
	v_mfma_f32_16x16x32_bf16 v[76:79], v[104:107], v[206:209], v[76:79]
	v_mfma_f32_16x16x32_bf16 v[72:75], v[148:151], v[206:209], v[72:75]
	v_mfma_f32_16x16x32_bf16 v[132:135], v[108:111], v[186:189], v[132:135]
	v_mfma_f32_16x16x32_bf16 v[128:131], v[152:155], v[186:189], v[128:131]
	v_mfma_f32_16x16x32_bf16 v[116:119], v[108:111], v[194:197], v[116:119]
	v_mfma_f32_16x16x32_bf16 v[112:115], v[152:155], v[194:197], v[112:115]
	v_mfma_f32_16x16x32_bf16 v[92:95], v[108:111], v[202:205], v[92:95]
	v_mfma_f32_16x16x32_bf16 v[88:91], v[152:155], v[202:205], v[88:91]
	v_mfma_f32_16x16x32_bf16 v[76:79], v[108:111], v[210:213], v[76:79]
	v_mfma_f32_16x16x32_bf16 v[72:75], v[152:155], v[210:213], v[72:75]
	s_setprio 0
	s_setprio 1
	v_mfma_f32_16x16x32_bf16 v[124:127], v[166:169], v[182:185], v[124:127]
	v_mfma_f32_16x16x32_bf16 v[120:123], v[174:177], v[182:185], v[120:123]
	v_mfma_f32_16x16x32_bf16 v[100:103], v[166:169], v[190:193], v[100:103]
	v_mfma_f32_16x16x32_bf16 v[96:99], v[174:177], v[190:193], v[96:99]
	v_mfma_f32_16x16x32_bf16 v[84:87], v[166:169], v[198:201], v[84:87]
	v_mfma_f32_16x16x32_bf16 v[80:83], v[174:177], v[198:201], v[80:83]
	v_mfma_f32_16x16x32_bf16 v[68:71], v[166:169], v[206:209], v[68:71]
	v_mfma_f32_16x16x32_bf16 v[64:67], v[174:177], v[206:209], v[64:67]
	v_mfma_f32_16x16x32_bf16 v[124:127], v[170:173], v[186:189], v[124:127]
	v_mfma_f32_16x16x32_bf16 v[120:123], v[178:181], v[186:189], v[120:123]
	v_mfma_f32_16x16x32_bf16 v[100:103], v[170:173], v[194:197], v[100:103]
	v_mfma_f32_16x16x32_bf16 v[96:99], v[178:181], v[194:197], v[96:99]
	v_mfma_f32_16x16x32_bf16 v[84:87], v[170:173], v[202:205], v[84:87]
	v_mfma_f32_16x16x32_bf16 v[80:83], v[178:181], v[202:205], v[80:83]
	v_mfma_f32_16x16x32_bf16 v[68:71], v[170:173], v[210:213], v[68:71]
	v_mfma_f32_16x16x32_bf16 v[64:67], v[178:181], v[210:213], v[64:67]
	s_setprio 0
	s_barrier
; #define PG8_STAGE(bufoff, gbase, voff) do { _Pragma("unroll") for (int _i = 0; _i < 2; ++_i) \
;         __builtin_amdgcn_global_load_lds((const unsigned*)((const char*)(gbase) + (voff)[_i]), (PG8_LAS unsigned*)(lds + (bufoff) + ldsw + _i * 8192), 16, 0, 0); } while (0)
; #define PG8_LDA(dst, b, h) do { _Pragma("unroll") for (int m = 0; m < 4; ++m) _Pragma("unroll") for (int k = 0; k < 2; ++k) dst[m][k] = *(const PG8_LAS bf16x8*)(lds + PG8_SA(b, h) + aoff + m * 2048 + k * 1024); } while (0)
; #define PG8_MMA(ai, bj, At, Bt) do { __builtin_amdgcn_s_setprio(1); _Pragma("unroll") for (int m = 0; m < 4; ++m) _Pragma("unroll") for (int n = 0; n < 2; ++n) _Pragma("unroll") for (int k = 0; k < 2; ++k) \
;         acc[ai][bj][m][n] = __builtin_amdgcn_mfma_f32_16x16x32_bf16(Bt[n][k], At[m][k], acc[ai][bj][m][n], 0, 0, 0); __builtin_amdgcn_s_setprio(0); } while (0)
; #define PG8_WAIT_V(n) asm volatile("s_waitcnt vmcnt(" #n ")" ::: "memory")
; #define PG8_WAIT_L(n) asm volatile("s_waitcnt lgkmcnt(" #n ")" ::: "memory")
; #define PG8_BAR __builtin_amdgcn_s_barrier()
; #define PG8_SCHED __builtin_amdgcn_sched_barrier(0)
; template <class Epi, class Sched, bool ALIGN_EPI = false, bool SP2 = false>
; __device__ __forceinline__ void gemm_phase(PG8_LAS unsigned char* lds, const Gemm g, const Sched& S, const Epi& E, const int wid) {
;     ...
;         for (int t = 0; t < nt; t += 2) {
;             const bool last = (t == nt - 2);
;             const char* a1 = cA + (size_t)(t + 1) * kstep;
;             const char* a2 = last ? nA : cA + (size_t)(t + 2) * kstep; const char* b2 = last ? nB : cB + (size_t)(t + 2) * kstep;
;     ...
;             PG8_LDA(At, 1, 1); PG8_STAGE(PG8_SB(1, 0), b3, voffB); PG8_STAGE(PG8_SB(1, 1), b3 + hstep, voffB); PG8_STAGE(PG8_SA(1, 0), a3, voffA);
;             PG8_WAIT_V(8); PG8_WAIT_L(0); PG8_BAR; PG8_MMA(1, 0, At, B0); PG8_MMA(1, 1, At, B1); PG8_BAR; PG8_SCHED;
	s_add_i32 s42, s70, s44
	v_lshl_add_u64 v[156:157], v[156:157], 0, s[6:7]
	s_mov_b32 m0, s42
	ds_read_b128 v[182:185], v163 offset:49152
	ds_read_b128 v[186:189], v163 offset:50176
	ds_read_b128 v[190:193], v163 offset:51200
	ds_read_b128 v[194:197], v163 offset:52224
	ds_read_b128 v[198:201], v163 offset:53248
	ds_read_b128 v[202:205], v163 offset:54272
	ds_read_b128 v[206:209], v163 offset:55296
	ds_read_b128 v[210:213], v163 offset:56320
	global_load_lds_dwordx4 v[156:157], off
	s_add_i32 m0, s42, 0x2000
	s_add_u32 s40, s40, 0x40080
	v_lshl_add_u64 v[156:157], v[214:215], 0, s[6:7]
	s_addc_u32 s41, s41, 0
	s_add_i32 s42, s71, s44
	global_load_lds_dwordx4 v[156:157], off
	s_mov_b32 m0, s42
	s_nop 0
	global_load_lds_dwordx4 v136, s[40:41]
	s_add_i32 m0, s42, 0x2000
	s_nop 0
	global_load_lds_dwordx4 v138, s[40:41]
	v_lshl_add_u64 v[156:157], v[216:217], 0, s[6:7]
	s_mov_b32 m0, s51
	s_nop 0
	global_load_lds_dwordx4 v[156:157], off
	v_lshl_add_u64 v[156:157], v[218:219], 0, s[6:7]
	s_mov_b32 m0, s52
	s_nop 0
	global_load_lds_dwordx4 v[156:157], off
	s_waitcnt vmcnt(8)
	s_waitcnt lgkmcnt(0)
	s_barrier
	s_setprio 1
	s_waitcnt lgkmcnt(0)
	v_mfma_f32_16x16x32_bf16 v[60:63], v[104:107], v[182:185], v[60:63]
	v_mfma_f32_16x16x32_bf16 v[56:59], v[148:151], v[182:185], v[56:59]
	v_mfma_f32_16x16x32_bf16 v[44:47], v[104:107], v[190:193], v[44:47]
	v_mfma_f32_16x16x32_bf16 v[40:43], v[148:151], v[190:193], v[40:43]
	v_mfma_f32_16x16x32_bf16 v[28:31], v[104:107], v[198:201], v[28:31]
	v_mfma_f32_16x16x32_bf16 v[24:27], v[148:151], v[198:201], v[24:27]
	v_mfma_f32_16x16x32_bf16 v[20:23], v[104:107], v[206:209], v[20:23]
	v_mfma_f32_16x16x32_bf16 v[12:15], v[148:151], v[206:209], v[12:15]
	v_mfma_f32_16x16x32_bf16 v[60:63], v[108:111], v[186:189], v[60:63]
	v_mfma_f32_16x16x32_bf16 v[56:59], v[152:155], v[186:189], v[56:59]
	v_mfma_f32_16x16x32_bf16 v[44:47], v[108:111], v[194:197], v[44:47]
	v_mfma_f32_16x16x32_bf16 v[40:43], v[152:155], v[194:197], v[40:43]
	v_mfma_f32_16x16x32_bf16 v[28:31], v[108:111], v[202:205], v[28:31]
	v_mfma_f32_16x16x32_bf16 v[24:27], v[152:155], v[202:205], v[24:27]
	v_mfma_f32_16x16x32_bf16 v[20:23], v[108:111], v[210:213], v[20:23]
	v_mfma_f32_16x16x32_bf16 v[12:15], v[152:155], v[210:213], v[12:15]
	s_setprio 0
	s_setprio 1
	v_mfma_f32_16x16x32_bf16 v[52:55], v[166:169], v[182:185], v[52:55]
	v_mfma_f32_16x16x32_bf16 v[48:51], v[174:177], v[182:185], v[48:51]
	v_mfma_f32_16x16x32_bf16 v[36:39], v[166:169], v[190:193], v[36:39]
	v_mfma_f32_16x16x32_bf16 v[32:35], v[174:177], v[190:193], v[32:35]
	v_mfma_f32_16x16x32_bf16 v[16:19], v[166:169], v[198:201], v[16:19]
	v_mfma_f32_16x16x32_bf16 v[8:11], v[174:177], v[198:201], v[8:11]
	v_mfma_f32_16x16x32_bf16 v[4:7], v[166:169], v[206:209], v[4:7]
	v_mfma_f32_16x16x32_bf16 v[0:3], v[174:177], v[206:209], v[0:3]
	v_mfma_f32_16x16x32_bf16 v[52:55], v[170:173], v[186:189], v[52:55]
	v_mfma_f32_16x16x32_bf16 v[48:51], v[178:181], v[186:189], v[48:51]
	v_mfma_f32_16x16x32_bf16 v[36:39], v[170:173], v[194:197], v[36:39]
	v_mfma_f32_16x16x32_bf16 v[32:35], v[178:181], v[194:197], v[32:35]
	v_mfma_f32_16x16x32_bf16 v[16:19], v[170:173], v[202:205], v[16:19]
	v_mfma_f32_16x16x32_bf16 v[8:11], v[178:181], v[202:205], v[8:11]
	v_mfma_f32_16x16x32_bf16 v[4:7], v[170:173], v[210:213], v[4:7]
	v_mfma_f32_16x16x32_bf16 v[0:3], v[178:181], v[210:213], v[0:3]
	s_setprio 0
	s_barrier
	s_add_i32 s69, s69, 2
	s_add_u32 s38, s38, 0x100
	s_addc_u32 s39, s39, 0
	s_add_u32 s67, s67, 0x100
	s_addc_u32 s68, s68, 0
	s_cmp_gt_u32 s69, 13
	s_cbranch_scc0 .LBB0_816
	s_and_b64 vcc, exec, s[8:9]
	s_cbranch_vccz .LBB0_819
	s_barrier
